# speedup vs baseline: 1.0212x; 1.0212x over previous
.LBB0_632:
	s_or_b64 exec, exec, s[0:1]
	v_lshlrev_b32_e32 v8, 16, v4
	v_and_b32_e32 v9, 0xffff0000, v4
	v_pk_add_f32 v[6:7], v[6:7], v[8:9] neg_lo:[0,1] neg_hi:[0,1]
	v_lshlrev_b32_e32 v8, 16, v5
	v_and_b32_e32 v9, 0xffff0000, v5
	v_pk_add_f32 v[2:3], v[2:3], v[8:9] neg_lo:[0,1] neg_hi:[0,1]
	v_cvt_pk_bf16_f32 v6, v6, v7
	v_cvt_pk_bf16_f32 v7, v2, v3
	ds_write_b64 v0, v[4:5] offset:1536
	ds_write_b64 v0, v[6:7] offset:34560
	v_lshrrev_b32_e32 v0, 1, v89
	v_and_b32_e32 v2, 24, v0
	v_and_b32_e32 v40, 15, v89
	v_lshl_or_b32 v34, s16, 8, v2
	v_lshlrev_b32_e32 v0, 11, v40
	v_ashrrev_i32_e32 v35, 31, v34
	v_readlane_b32 s0, v207, 26
	v_lshl_add_u64 v[30:31], s[40:41], 0, v[0:1]
	v_lshl_add_u64 v[32:33], s[44:45], 0, v[0:1]
	v_lshl_add_u64 v[2:3], v[34:35], 1, v[0:1]
	v_readlane_b32 s1, v207, 27
	v_and_b32_e32 v0, 48, v89
	v_mul_u32_u24_e32 v4, 0x408, v40
	v_lshl_add_u64 v[36:37], s[0:1], 0, v[2:3]
	v_lshl_or_b32 v0, s16, 9, v0
	v_mov_b32_e32 v2, 0
	v_lshl_add_u32 v0, v4, 1, v0
	s_mov_b64 s[0:1], 0
	v_mov_b32_e32 v3, v2
	v_mov_b32_e32 v4, v2
	v_mov_b32_e32 v5, v2
	v_mov_b32_e32 v10, v2
	v_mov_b32_e32 v11, v2
	v_mov_b32_e32 v12, v2
	v_mov_b32_e32 v13, v2
	v_mov_b32_e32 v14, v2
	v_mov_b32_e32 v15, v2
	v_mov_b32_e32 v16, v2
	v_mov_b32_e32 v17, v2
	v_mov_b32_e32 v18, v2
	v_mov_b32_e32 v19, v2
	v_mov_b32_e32 v20, v2
	v_mov_b32_e32 v21, v2
	v_mov_b32_e32 v6, v2
	v_mov_b32_e32 v7, v2
	v_mov_b32_e32 v8, v2
	v_mov_b32_e32 v9, v2
	v_ashrrev_i32_e32 v35, 31, v34
	v_lshlrev_b64 v[38:39], 1, v[34:35]
	v_lshl_add_u64 v[50:51], v[30:31], 0, v[38:39]
	v_lshl_add_u64 v[38:39], v[32:33], 0, v[38:39]
	s_mov_b32 s98, 0x8000
	s_mov_b32 s99, 0
	global_load_dwordx4 v[210:213], v[50:51], off
	global_load_dwordx4 v[230:233], v[38:39], off
	v_lshl_add_u64 v[250:251], v[50:51], 0, s[98:99]
	v_lshl_add_u64 v[252:253], v[38:39], 0, s[98:99]
	global_load_dwordx4 v[214:217], v[250:251], off
	global_load_dwordx4 v[234:237], v[252:253], off
	v_lshl_add_u64 v[250:251], v[250:251], 0, s[98:99]
	v_lshl_add_u64 v[252:253], v[252:253], 0, s[98:99]
	global_load_dwordx4 v[218:221], v[250:251], off
	global_load_dwordx4 v[238:241], v[252:253], off
	v_lshl_add_u64 v[250:251], v[250:251], 0, s[98:99]
	v_lshl_add_u64 v[252:253], v[252:253], 0, s[98:99]
	global_load_dwordx4 v[222:225], v[250:251], off
	global_load_dwordx4 v[242:245], v[252:253], off
	v_lshl_add_u64 v[250:251], v[250:251], 0, s[98:99]
	v_lshl_add_u64 v[252:253], v[252:253], 0, s[98:99]
	global_load_dwordx4 v[226:229], v[250:251], off
	global_load_dwordx4 v[246:249], v[252:253], off
	s_waitcnt lgkmcnt(0)
	s_barrier
.LBB0_633:
	ds_read_b128 v[22:25], v0
	ds_read_b128 v[26:29], v0 offset:33024
	s_waitcnt vmcnt(9) lgkmcnt(1)
	v_mfma_f32_16x16x32_bf16 v[2:5], v[210:213], v[22:25], v[2:5]
	s_waitcnt lgkmcnt(0)
	v_mfma_f32_16x16x32_bf16 v[2:5], v[210:213], v[26:29], v[2:5]
	s_waitcnt vmcnt(8)
	v_mfma_f32_16x16x32_bf16 v[2:5], v[230:233], v[22:25], v[2:5]
	global_load_dwordx4 v[210:213], v[50:51], off offset:64
	global_load_dwordx4 v[230:233], v[38:39], off offset:64
	s_waitcnt vmcnt(9)
	v_mfma_f32_16x16x32_bf16 v[10:13], v[214:217], v[22:25], v[10:13]
	v_mfma_f32_16x16x32_bf16 v[10:13], v[214:217], v[26:29], v[10:13]
	s_waitcnt vmcnt(8)
	v_mfma_f32_16x16x32_bf16 v[10:13], v[234:237], v[22:25], v[10:13]
	v_lshl_add_u64 v[250:251], v[50:51], 0, s[98:99]
	v_lshl_add_u64 v[252:253], v[38:39], 0, s[98:99]
	global_load_dwordx4 v[214:217], v[250:251], off offset:64
	global_load_dwordx4 v[234:237], v[252:253], off offset:64
	s_waitcnt vmcnt(9)
	v_mfma_f32_16x16x32_bf16 v[14:17], v[218:221], v[22:25], v[14:17]
	v_mfma_f32_16x16x32_bf16 v[14:17], v[218:221], v[26:29], v[14:17]
	s_waitcnt vmcnt(8)
	v_mfma_f32_16x16x32_bf16 v[14:17], v[238:241], v[22:25], v[14:17]
	v_lshl_add_u64 v[250:251], v[250:251], 0, s[98:99]
	v_lshl_add_u64 v[252:253], v[252:253], 0, s[98:99]
	global_load_dwordx4 v[218:221], v[250:251], off offset:64
	global_load_dwordx4 v[238:241], v[252:253], off offset:64
	s_waitcnt vmcnt(9)
	v_mfma_f32_16x16x32_bf16 v[18:21], v[222:225], v[22:25], v[18:21]
	v_mfma_f32_16x16x32_bf16 v[18:21], v[222:225], v[26:29], v[18:21]
	s_waitcnt vmcnt(8)
	v_mfma_f32_16x16x32_bf16 v[18:21], v[242:245], v[22:25], v[18:21]
	v_lshl_add_u64 v[250:251], v[250:251], 0, s[98:99]
	v_lshl_add_u64 v[252:253], v[252:253], 0, s[98:99]
	global_load_dwordx4 v[222:225], v[250:251], off offset:64
	global_load_dwordx4 v[242:245], v[252:253], off offset:64
	s_waitcnt vmcnt(9)
	v_mfma_f32_16x16x32_bf16 v[6:9], v[226:229], v[22:25], v[6:9]
	v_mfma_f32_16x16x32_bf16 v[6:9], v[226:229], v[26:29], v[6:9]
	s_waitcnt vmcnt(8)
	v_mfma_f32_16x16x32_bf16 v[6:9], v[246:249], v[22:25], v[6:9]
	v_lshl_add_u64 v[250:251], v[250:251], 0, s[98:99]
	v_lshl_add_u64 v[252:253], v[252:253], 0, s[98:99]
	global_load_dwordx4 v[226:229], v[250:251], off offset:64
	global_load_dwordx4 v[246:249], v[252:253], off offset:64
	ds_read_b128 v[22:25], v0 offset:64
	ds_read_b128 v[26:29], v0 offset:33088
	s_waitcnt vmcnt(9) lgkmcnt(1)
	v_mfma_f32_16x16x32_bf16 v[2:5], v[210:213], v[22:25], v[2:5]
	s_waitcnt lgkmcnt(0)
	v_mfma_f32_16x16x32_bf16 v[2:5], v[210:213], v[26:29], v[2:5]
	s_waitcnt vmcnt(8)
	v_mfma_f32_16x16x32_bf16 v[2:5], v[230:233], v[22:25], v[2:5]
	global_load_dwordx4 v[210:213], v[50:51], off offset:128
	global_load_dwordx4 v[230:233], v[38:39], off offset:128
	s_waitcnt vmcnt(9)
	v_mfma_f32_16x16x32_bf16 v[10:13], v[214:217], v[22:25], v[10:13]
	v_mfma_f32_16x16x32_bf16 v[10:13], v[214:217], v[26:29], v[10:13]
	s_waitcnt vmcnt(8)
	v_mfma_f32_16x16x32_bf16 v[10:13], v[234:237], v[22:25], v[10:13]
	v_lshl_add_u64 v[250:251], v[50:51], 0, s[98:99]
	v_lshl_add_u64 v[252:253], v[38:39], 0, s[98:99]
	global_load_dwordx4 v[214:217], v[250:251], off offset:128
	global_load_dwordx4 v[234:237], v[252:253], off offset:128
	s_waitcnt vmcnt(9)
	v_mfma_f32_16x16x32_bf16 v[14:17], v[218:221], v[22:25], v[14:17]
	v_mfma_f32_16x16x32_bf16 v[14:17], v[218:221], v[26:29], v[14:17]
	s_waitcnt vmcnt(8)
	v_mfma_f32_16x16x32_bf16 v[14:17], v[238:241], v[22:25], v[14:17]
	v_lshl_add_u64 v[250:251], v[250:251], 0, s[98:99]
	v_lshl_add_u64 v[252:253], v[252:253], 0, s[98:99]
	global_load_dwordx4 v[218:221], v[250:251], off offset:128
	global_load_dwordx4 v[238:241], v[252:253], off offset:128
	s_waitcnt vmcnt(9)
	v_mfma_f32_16x16x32_bf16 v[18:21], v[222:225], v[22:25], v[18:21]
	v_mfma_f32_16x16x32_bf16 v[18:21], v[222:225], v[26:29], v[18:21]
	s_waitcnt vmcnt(8)
	v_mfma_f32_16x16x32_bf16 v[18:21], v[242:245], v[22:25], v[18:21]
	v_lshl_add_u64 v[250:251], v[250:251], 0, s[98:99]
	v_lshl_add_u64 v[252:253], v[252:253], 0, s[98:99]
	global_load_dwordx4 v[222:225], v[250:251], off offset:128
	global_load_dwordx4 v[242:245], v[252:253], off offset:128
	s_waitcnt vmcnt(9)
	v_mfma_f32_16x16x32_bf16 v[6:9], v[226:229], v[22:25], v[6:9]
	v_mfma_f32_16x16x32_bf16 v[6:9], v[226:229], v[26:29], v[6:9]
	s_waitcnt vmcnt(8)
	v_mfma_f32_16x16x32_bf16 v[6:9], v[246:249], v[22:25], v[6:9]
	v_lshl_add_u64 v[250:251], v[250:251], 0, s[98:99]
	v_lshl_add_u64 v[252:253], v[252:253], 0, s[98:99]
	global_load_dwordx4 v[226:229], v[250:251], off offset:128
	global_load_dwordx4 v[246:249], v[252:253], off offset:128
	ds_read_b128 v[22:25], v0 offset:128
	ds_read_b128 v[26:29], v0 offset:33152
	s_waitcnt vmcnt(9) lgkmcnt(1)
	v_mfma_f32_16x16x32_bf16 v[2:5], v[210:213], v[22:25], v[2:5]
	s_waitcnt lgkmcnt(0)
	v_mfma_f32_16x16x32_bf16 v[2:5], v[210:213], v[26:29], v[2:5]
	s_waitcnt vmcnt(8)
	v_mfma_f32_16x16x32_bf16 v[2:5], v[230:233], v[22:25], v[2:5]
	global_load_dwordx4 v[210:213], v[50:51], off offset:192
	global_load_dwordx4 v[230:233], v[38:39], off offset:192
	s_waitcnt vmcnt(9)
	v_mfma_f32_16x16x32_bf16 v[10:13], v[214:217], v[22:25], v[10:13]
	v_mfma_f32_16x16x32_bf16 v[10:13], v[214:217], v[26:29], v[10:13]
	s_waitcnt vmcnt(8)
	v_mfma_f32_16x16x32_bf16 v[10:13], v[234:237], v[22:25], v[10:13]
	v_lshl_add_u64 v[250:251], v[50:51], 0, s[98:99]
	v_lshl_add_u64 v[252:253], v[38:39], 0, s[98:99]
	global_load_dwordx4 v[214:217], v[250:251], off offset:192
	global_load_dwordx4 v[234:237], v[252:253], off offset:192
	s_waitcnt vmcnt(9)
	v_mfma_f32_16x16x32_bf16 v[14:17], v[218:221], v[22:25], v[14:17]
	v_mfma_f32_16x16x32_bf16 v[14:17], v[218:221], v[26:29], v[14:17]
	s_waitcnt vmcnt(8)
	v_mfma_f32_16x16x32_bf16 v[14:17], v[238:241], v[22:25], v[14:17]
	v_lshl_add_u64 v[250:251], v[250:251], 0, s[98:99]
	v_lshl_add_u64 v[252:253], v[252:253], 0, s[98:99]
	global_load_dwordx4 v[218:221], v[250:251], off offset:192
	global_load_dwordx4 v[238:241], v[252:253], off offset:192
	s_waitcnt vmcnt(9)
	v_mfma_f32_16x16x32_bf16 v[18:21], v[222:225], v[22:25], v[18:21]
	v_mfma_f32_16x16x32_bf16 v[18:21], v[222:225], v[26:29], v[18:21]
	s_waitcnt vmcnt(8)
	v_mfma_f32_16x16x32_bf16 v[18:21], v[242:245], v[22:25], v[18:21]
	v_lshl_add_u64 v[250:251], v[250:251], 0, s[98:99]
	v_lshl_add_u64 v[252:253], v[252:253], 0, s[98:99]
	global_load_dwordx4 v[222:225], v[250:251], off offset:192
	global_load_dwordx4 v[242:245], v[252:253], off offset:192
	s_waitcnt vmcnt(9)
	v_mfma_f32_16x16x32_bf16 v[6:9], v[226:229], v[22:25], v[6:9]
	v_mfma_f32_16x16x32_bf16 v[6:9], v[226:229], v[26:29], v[6:9]
	s_waitcnt vmcnt(8)
	v_mfma_f32_16x16x32_bf16 v[6:9], v[246:249], v[22:25], v[6:9]
	v_lshl_add_u64 v[250:251], v[250:251], 0, s[98:99]
	v_lshl_add_u64 v[252:253], v[252:253], 0, s[98:99]
	global_load_dwordx4 v[226:229], v[250:251], off offset:192
	global_load_dwordx4 v[246:249], v[252:253], off offset:192
	ds_read_b128 v[22:25], v0 offset:192
	ds_read_b128 v[26:29], v0 offset:33216
	s_waitcnt vmcnt(9) lgkmcnt(1)
	v_mfma_f32_16x16x32_bf16 v[2:5], v[210:213], v[22:25], v[2:5]
	s_waitcnt lgkmcnt(0)
	v_mfma_f32_16x16x32_bf16 v[2:5], v[210:213], v[26:29], v[2:5]
	s_waitcnt vmcnt(8)
	v_mfma_f32_16x16x32_bf16 v[2:5], v[230:233], v[22:25], v[2:5]
	global_load_dwordx4 v[210:213], v[50:51], off offset:256
	global_load_dwordx4 v[230:233], v[38:39], off offset:256
	s_waitcnt vmcnt(9)
	v_mfma_f32_16x16x32_bf16 v[10:13], v[214:217], v[22:25], v[10:13]
	v_mfma_f32_16x16x32_bf16 v[10:13], v[214:217], v[26:29], v[10:13]
	s_waitcnt vmcnt(8)
	v_mfma_f32_16x16x32_bf16 v[10:13], v[234:237], v[22:25], v[10:13]
	v_lshl_add_u64 v[250:251], v[50:51], 0, s[98:99]
	v_lshl_add_u64 v[252:253], v[38:39], 0, s[98:99]
	global_load_dwordx4 v[214:217], v[250:251], off offset:256
	global_load_dwordx4 v[234:237], v[252:253], off offset:256
	s_waitcnt vmcnt(9)
	v_mfma_f32_16x16x32_bf16 v[14:17], v[218:221], v[22:25], v[14:17]
	v_mfma_f32_16x16x32_bf16 v[14:17], v[218:221], v[26:29], v[14:17]
	s_waitcnt vmcnt(8)
	v_mfma_f32_16x16x32_bf16 v[14:17], v[238:241], v[22:25], v[14:17]
	v_lshl_add_u64 v[250:251], v[250:251], 0, s[98:99]
	v_lshl_add_u64 v[252:253], v[252:253], 0, s[98:99]
	global_load_dwordx4 v[218:221], v[250:251], off offset:256
	global_load_dwordx4 v[238:241], v[252:253], off offset:256
	s_waitcnt vmcnt(9)
	v_mfma_f32_16x16x32_bf16 v[18:21], v[222:225], v[22:25], v[18:21]
	v_mfma_f32_16x16x32_bf16 v[18:21], v[222:225], v[26:29], v[18:21]
	s_waitcnt vmcnt(8)
	v_mfma_f32_16x16x32_bf16 v[18:21], v[242:245], v[22:25], v[18:21]
	v_lshl_add_u64 v[250:251], v[250:251], 0, s[98:99]
	v_lshl_add_u64 v[252:253], v[252:253], 0, s[98:99]
	global_load_dwordx4 v[222:225], v[250:251], off offset:256
	global_load_dwordx4 v[242:245], v[252:253], off offset:256
	s_waitcnt vmcnt(9)
	v_mfma_f32_16x16x32_bf16 v[6:9], v[226:229], v[22:25], v[6:9]
	v_mfma_f32_16x16x32_bf16 v[6:9], v[226:229], v[26:29], v[6:9]
	s_waitcnt vmcnt(8)
	v_mfma_f32_16x16x32_bf16 v[6:9], v[246:249], v[22:25], v[6:9]
	v_lshl_add_u64 v[250:251], v[250:251], 0, s[98:99]
	v_lshl_add_u64 v[252:253], v[252:253], 0, s[98:99]
	global_load_dwordx4 v[226:229], v[250:251], off offset:256
	global_load_dwordx4 v[246:249], v[252:253], off offset:256
	ds_read_b128 v[22:25], v0 offset:256
	ds_read_b128 v[26:29], v0 offset:33280
	s_waitcnt vmcnt(9) lgkmcnt(1)
	v_mfma_f32_16x16x32_bf16 v[2:5], v[210:213], v[22:25], v[2:5]
	s_waitcnt lgkmcnt(0)
	v_mfma_f32_16x16x32_bf16 v[2:5], v[210:213], v[26:29], v[2:5]
	s_waitcnt vmcnt(8)
	v_mfma_f32_16x16x32_bf16 v[2:5], v[230:233], v[22:25], v[2:5]
	global_load_dwordx4 v[210:213], v[50:51], off offset:320
	global_load_dwordx4 v[230:233], v[38:39], off offset:320
	s_waitcnt vmcnt(9)
	v_mfma_f32_16x16x32_bf16 v[10:13], v[214:217], v[22:25], v[10:13]
	v_mfma_f32_16x16x32_bf16 v[10:13], v[214:217], v[26:29], v[10:13]
	s_waitcnt vmcnt(8)
	v_mfma_f32_16x16x32_bf16 v[10:13], v[234:237], v[22:25], v[10:13]
	v_lshl_add_u64 v[250:251], v[50:51], 0, s[98:99]
	v_lshl_add_u64 v[252:253], v[38:39], 0, s[98:99]
	global_load_dwordx4 v[214:217], v[250:251], off offset:320
	global_load_dwordx4 v[234:237], v[252:253], off offset:320
	s_waitcnt vmcnt(9)
	v_mfma_f32_16x16x32_bf16 v[14:17], v[218:221], v[22:25], v[14:17]
	v_mfma_f32_16x16x32_bf16 v[14:17], v[218:221], v[26:29], v[14:17]
	s_waitcnt vmcnt(8)
	v_mfma_f32_16x16x32_bf16 v[14:17], v[238:241], v[22:25], v[14:17]
	v_lshl_add_u64 v[250:251], v[250:251], 0, s[98:99]
	v_lshl_add_u64 v[252:253], v[252:253], 0, s[98:99]
	global_load_dwordx4 v[218:221], v[250:251], off offset:320
	global_load_dwordx4 v[238:241], v[252:253], off offset:320
	s_waitcnt vmcnt(9)
	v_mfma_f32_16x16x32_bf16 v[18:21], v[222:225], v[22:25], v[18:21]
	v_mfma_f32_16x16x32_bf16 v[18:21], v[222:225], v[26:29], v[18:21]
	s_waitcnt vmcnt(8)
	v_mfma_f32_16x16x32_bf16 v[18:21], v[242:245], v[22:25], v[18:21]
	v_lshl_add_u64 v[250:251], v[250:251], 0, s[98:99]
	v_lshl_add_u64 v[252:253], v[252:253], 0, s[98:99]
	global_load_dwordx4 v[222:225], v[250:251], off offset:320
	global_load_dwordx4 v[242:245], v[252:253], off offset:320
	s_waitcnt vmcnt(9)
	v_mfma_f32_16x16x32_bf16 v[6:9], v[226:229], v[22:25], v[6:9]
	v_mfma_f32_16x16x32_bf16 v[6:9], v[226:229], v[26:29], v[6:9]
	s_waitcnt vmcnt(8)
	v_mfma_f32_16x16x32_bf16 v[6:9], v[246:249], v[22:25], v[6:9]
	v_lshl_add_u64 v[250:251], v[250:251], 0, s[98:99]
	v_lshl_add_u64 v[252:253], v[252:253], 0, s[98:99]
	global_load_dwordx4 v[226:229], v[250:251], off offset:320
	global_load_dwordx4 v[246:249], v[252:253], off offset:320
	ds_read_b128 v[22:25], v0 offset:320
	ds_read_b128 v[26:29], v0 offset:33344
	s_waitcnt vmcnt(9) lgkmcnt(1)
	v_mfma_f32_16x16x32_bf16 v[2:5], v[210:213], v[22:25], v[2:5]
	s_waitcnt lgkmcnt(0)
	v_mfma_f32_16x16x32_bf16 v[2:5], v[210:213], v[26:29], v[2:5]
	s_waitcnt vmcnt(8)
	v_mfma_f32_16x16x32_bf16 v[2:5], v[230:233], v[22:25], v[2:5]
	global_load_dwordx4 v[210:213], v[50:51], off offset:384
	global_load_dwordx4 v[230:233], v[38:39], off offset:384
	s_waitcnt vmcnt(9)
	v_mfma_f32_16x16x32_bf16 v[10:13], v[214:217], v[22:25], v[10:13]
	v_mfma_f32_16x16x32_bf16 v[10:13], v[214:217], v[26:29], v[10:13]
	s_waitcnt vmcnt(8)
	v_mfma_f32_16x16x32_bf16 v[10:13], v[234:237], v[22:25], v[10:13]
	v_lshl_add_u64 v[250:251], v[50:51], 0, s[98:99]
	v_lshl_add_u64 v[252:253], v[38:39], 0, s[98:99]
	global_load_dwordx4 v[214:217], v[250:251], off offset:384
	global_load_dwordx4 v[234:237], v[252:253], off offset:384
	s_waitcnt vmcnt(9)
	v_mfma_f32_16x16x32_bf16 v[14:17], v[218:221], v[22:25], v[14:17]
	v_mfma_f32_16x16x32_bf16 v[14:17], v[218:221], v[26:29], v[14:17]
	s_waitcnt vmcnt(8)
	v_mfma_f32_16x16x32_bf16 v[14:17], v[238:241], v[22:25], v[14:17]
	v_lshl_add_u64 v[250:251], v[250:251], 0, s[98:99]
	v_lshl_add_u64 v[252:253], v[252:253], 0, s[98:99]
	global_load_dwordx4 v[218:221], v[250:251], off offset:384
	global_load_dwordx4 v[238:241], v[252:253], off offset:384
	s_waitcnt vmcnt(9)
	v_mfma_f32_16x16x32_bf16 v[18:21], v[222:225], v[22:25], v[18:21]
	v_mfma_f32_16x16x32_bf16 v[18:21], v[222:225], v[26:29], v[18:21]
	s_waitcnt vmcnt(8)
	v_mfma_f32_16x16x32_bf16 v[18:21], v[242:245], v[22:25], v[18:21]
	v_lshl_add_u64 v[250:251], v[250:251], 0, s[98:99]
	v_lshl_add_u64 v[252:253], v[252:253], 0, s[98:99]
	global_load_dwordx4 v[222:225], v[250:251], off offset:384
	global_load_dwordx4 v[242:245], v[252:253], off offset:384
	s_waitcnt vmcnt(9)
	v_mfma_f32_16x16x32_bf16 v[6:9], v[226:229], v[22:25], v[6:9]
	v_mfma_f32_16x16x32_bf16 v[6:9], v[226:229], v[26:29], v[6:9]
	s_waitcnt vmcnt(8)
	v_mfma_f32_16x16x32_bf16 v[6:9], v[246:249], v[22:25], v[6:9]
	v_lshl_add_u64 v[250:251], v[250:251], 0, s[98:99]
	v_lshl_add_u64 v[252:253], v[252:253], 0, s[98:99]
	global_load_dwordx4 v[226:229], v[250:251], off offset:384
	global_load_dwordx4 v[246:249], v[252:253], off offset:384
	ds_read_b128 v[22:25], v0 offset:384
	ds_read_b128 v[26:29], v0 offset:33408
	s_waitcnt vmcnt(9) lgkmcnt(1)
	v_mfma_f32_16x16x32_bf16 v[2:5], v[210:213], v[22:25], v[2:5]
	s_waitcnt lgkmcnt(0)
	v_mfma_f32_16x16x32_bf16 v[2:5], v[210:213], v[26:29], v[2:5]
	s_waitcnt vmcnt(8)
	v_mfma_f32_16x16x32_bf16 v[2:5], v[230:233], v[22:25], v[2:5]
	global_load_dwordx4 v[210:213], v[50:51], off offset:448
	global_load_dwordx4 v[230:233], v[38:39], off offset:448
	s_waitcnt vmcnt(9)
	v_mfma_f32_16x16x32_bf16 v[10:13], v[214:217], v[22:25], v[10:13]
	v_mfma_f32_16x16x32_bf16 v[10:13], v[214:217], v[26:29], v[10:13]
	s_waitcnt vmcnt(8)
	v_mfma_f32_16x16x32_bf16 v[10:13], v[234:237], v[22:25], v[10:13]
	v_lshl_add_u64 v[250:251], v[50:51], 0, s[98:99]
	v_lshl_add_u64 v[252:253], v[38:39], 0, s[98:99]
	global_load_dwordx4 v[214:217], v[250:251], off offset:448
	global_load_dwordx4 v[234:237], v[252:253], off offset:448
	s_waitcnt vmcnt(9)
	v_mfma_f32_16x16x32_bf16 v[14:17], v[218:221], v[22:25], v[14:17]
	v_mfma_f32_16x16x32_bf16 v[14:17], v[218:221], v[26:29], v[14:17]
	s_waitcnt vmcnt(8)
	v_mfma_f32_16x16x32_bf16 v[14:17], v[238:241], v[22:25], v[14:17]
	v_lshl_add_u64 v[250:251], v[250:251], 0, s[98:99]
	v_lshl_add_u64 v[252:253], v[252:253], 0, s[98:99]
	global_load_dwordx4 v[218:221], v[250:251], off offset:448
	global_load_dwordx4 v[238:241], v[252:253], off offset:448
	s_waitcnt vmcnt(9)
	v_mfma_f32_16x16x32_bf16 v[18:21], v[222:225], v[22:25], v[18:21]
	v_mfma_f32_16x16x32_bf16 v[18:21], v[222:225], v[26:29], v[18:21]
	s_waitcnt vmcnt(8)
	v_mfma_f32_16x16x32_bf16 v[18:21], v[242:245], v[22:25], v[18:21]
	v_lshl_add_u64 v[250:251], v[250:251], 0, s[98:99]
	v_lshl_add_u64 v[252:253], v[252:253], 0, s[98:99]
	global_load_dwordx4 v[222:225], v[250:251], off offset:448
	global_load_dwordx4 v[242:245], v[252:253], off offset:448
	s_waitcnt vmcnt(9)
	v_mfma_f32_16x16x32_bf16 v[6:9], v[226:229], v[22:25], v[6:9]
	v_mfma_f32_16x16x32_bf16 v[6:9], v[226:229], v[26:29], v[6:9]
	s_waitcnt vmcnt(8)
	v_mfma_f32_16x16x32_bf16 v[6:9], v[246:249], v[22:25], v[6:9]
	v_lshl_add_u64 v[250:251], v[250:251], 0, s[98:99]
	v_lshl_add_u64 v[252:253], v[252:253], 0, s[98:99]
	global_load_dwordx4 v[226:229], v[250:251], off offset:448
	global_load_dwordx4 v[246:249], v[252:253], off offset:448
	ds_read_b128 v[22:25], v0 offset:448
	ds_read_b128 v[26:29], v0 offset:33472
	s_waitcnt vmcnt(9) lgkmcnt(1)
	v_mfma_f32_16x16x32_bf16 v[2:5], v[210:213], v[22:25], v[2:5]
	s_waitcnt lgkmcnt(0)
	v_mfma_f32_16x16x32_bf16 v[2:5], v[210:213], v[26:29], v[2:5]
	s_waitcnt vmcnt(8)
	v_mfma_f32_16x16x32_bf16 v[2:5], v[230:233], v[22:25], v[2:5]
	s_waitcnt vmcnt(7)
	v_mfma_f32_16x16x32_bf16 v[10:13], v[214:217], v[22:25], v[10:13]
	v_mfma_f32_16x16x32_bf16 v[10:13], v[214:217], v[26:29], v[10:13]
	s_waitcnt vmcnt(6)
	v_mfma_f32_16x16x32_bf16 v[10:13], v[234:237], v[22:25], v[10:13]
	s_waitcnt vmcnt(5)
	v_mfma_f32_16x16x32_bf16 v[14:17], v[218:221], v[22:25], v[14:17]
	v_mfma_f32_16x16x32_bf16 v[14:17], v[218:221], v[26:29], v[14:17]
	s_waitcnt vmcnt(4)
	v_mfma_f32_16x16x32_bf16 v[14:17], v[238:241], v[22:25], v[14:17]
	s_waitcnt vmcnt(3)
	v_mfma_f32_16x16x32_bf16 v[18:21], v[222:225], v[22:25], v[18:21]
	v_mfma_f32_16x16x32_bf16 v[18:21], v[222:225], v[26:29], v[18:21]
	s_waitcnt vmcnt(2)
	v_mfma_f32_16x16x32_bf16 v[18:21], v[242:245], v[22:25], v[18:21]
	s_waitcnt vmcnt(1)
	v_mfma_f32_16x16x32_bf16 v[6:9], v[226:229], v[22:25], v[6:9]
	v_mfma_f32_16x16x32_bf16 v[6:9], v[226:229], v[26:29], v[6:9]
	s_waitcnt vmcnt(0)
	v_mfma_f32_16x16x32_bf16 v[6:9], v[246:249], v[22:25], v[6:9]
	v_lshl_or_b32 v0, s16, 4, v40
	s_movk_i32 s0, 0x140
	v_mul_lo_u32 v0, v0, s0
	v_and_or_b32 v0, v89, 48, v0
	s_barrier
	ds_write_b128 v0, v[2:5]
	ds_write_b128 v0, v[10:13] offset:64
	ds_write_b128 v0, v[14:17] offset:128
	ds_write_b128 v0, v[18:21] offset:192
	ds_write_b128 v0, v[6:9] offset:256
	v_and_b32_e32 v0, 7, v89
	v_lshlrev_b32_e32 v11, 2, v0
	s_mulk_i32 s16, 0x500
	v_or_b32_e32 v4, s16, v11
	s_waitcnt lgkmcnt(0)
	s_barrier
	ds_read2st64_b32 v[2:3], v4 offset0:1 offset1:21
	ds_read2st64_b32 v[6:7], v4 offset0:41 offset1:61
	v_or_b32_e32 v8, s16, v72
	ds_read2st64_b32 v[4:5], v8 offset1:20
	ds_bpermute_b32 v10, v88, v0
	s_waitcnt lgkmcnt(3)
	v_add_f32_e32 v2, v2, v3
	s_waitcnt lgkmcnt(2)
	v_add_f32_e32 v2, v2, v6
	v_add_f32_e32 v6, v2, v7
	ds_bpermute_b32 v9, v88, v6
	ds_read2st64_b32 v[2:3], v8 offset0:40 offset1:60
	s_waitcnt lgkmcnt(1)
	v_cmp_lt_f32_e64 s[48:49], v6, v9
	v_cmp_nlt_f32_e32 vcc, v6, v9
	s_and_saveexec_b64 s[50:51], vcc
	v_cmp_eq_f32_e32 vcc, v6, v9
	v_cmp_lt_i32_e64 s[0:1], v10, v0
	s_and_b64 s[0:1], vcc, s[0:1]
	s_andn2_b64 s[48:49], s[48:49], exec
	s_and_b64 s[0:1], s[0:1], exec
	s_or_b64 s[48:49], s[48:49], s[0:1]
	s_or_b64 exec, exec, s[50:51]
	v_mov_b32_e32 v8, v6
	v_mov_b32_e32 v12, v0
	v_mov_b32_e32 v7, v6
	s_and_saveexec_b64 s[0:1], s[48:49]
	v_mov_b32_e32 v8, v9
	v_mov_b32_e32 v12, v10
	v_mov_b32_e32 v7, v9
	s_or_b64 exec, exec, s[0:1]
	ds_bpermute_b32 v9, v87, v8
	ds_bpermute_b32 v10, v87, v12
	s_waitcnt lgkmcnt(1)
	v_cmp_lt_f32_e64 s[48:49], v7, v9
	v_cmp_nlt_f32_e32 vcc, v7, v9
	s_and_saveexec_b64 s[50:51], vcc
	s_cbranch_execz .LBB0_640
	v_cmp_eq_f32_e32 vcc, v7, v9
	s_waitcnt lgkmcnt(0)
	v_cmp_lt_i32_e64 s[0:1], v10, v12
	s_and_b64 s[0:1], vcc, s[0:1]
	s_andn2_b64 s[48:49], s[48:49], exec
	s_and_b64 s[0:1], s[0:1], exec
	s_or_b64 s[48:49], s[48:49], s[0:1]

.LBB0_844:
	s_ashr_i32 s1, s14, 6
	s_and_b32 s0, s14, 7
	s_and_b32 s1, s1, 0xffffff8
	s_or_b32 s0, s1, s0
	s_lshl_b32 s0, s0, 4
	s_bfe_u32 s1, s14, 0x40005
	s_or_b32 s0, s0, s1
	s_cmpk_lt_i32 s14, 0x400
	s_cbranch_scc1 .Lp8a_eb_ok
	s_bfe_u32 s1, s14, 0x40005
	s_lshl_b32 s1, s1, 3
	s_and_b32 s0, s14, 7
	s_or_b32 s0, s0, s1
	s_addk_i32 s0, 0x100
.Lp8a_eb_ok:
	s_cmp_ge_i32 s0, s9
	s_cbranch_scc1 .LBB0_843
	ds_read_b32 v0, v169
	s_lshl_b32 s1, s13, 2
	s_and_b32 s34, s1, 0x300
	v_mov_b32_e32 v118, v144
	v_readlane_b32 s44, v209, 0
	s_waitcnt lgkmcnt(0)
	v_readfirstlane_b32 s1, v0
	s_cmp_gt_i32 s1, s0
	s_cselect_b32 s10, 0, 32
	s_lshl_b32 s15, s10, 2
	s_or_b32 s15, s15, 0x13040
	v_mov_b32_e32 v0, s15
	ds_read_b32 v0, v0
	s_or_b32 s11, s10, 16
	v_readlane_b32 s45, v209, 1
	v_readlane_b32 s47, v209, 3
	v_readlane_b32 s46, v209, 2
	s_waitcnt lgkmcnt(0)
	v_readfirstlane_b32 s15, v0
	s_cmp_gt_i32 s15, s0
	s_cselect_b32 s10, s10, s11
	s_lshl_b32 s15, s10, 2
	s_or_b32 s15, s15, 0x13020
	v_mov_b32_e32 v0, s15
	ds_read_b32 v0, v0
	s_or_b32 s11, s10, 8
	v_mov_b32_e32 v6, s45
	v_mov_b32_e32 v25, v1
	s_mov_b64 s[38:39], 0x2000
	s_waitcnt lgkmcnt(0)
	v_readfirstlane_b32 s15, v0
	s_cmp_gt_i32 s15, s0
	s_cselect_b32 s10, s10, s11
	s_lshl_b32 s15, s10, 2
	s_or_b32 s15, s15, 0x13010
	v_mov_b32_e32 v0, s15
	ds_read_b32 v0, v0
	s_or_b32 s11, s10, 4
	s_mov_b32 s1, 0
	v_readlane_b32 s48, v209, 4
	v_readlane_b32 s49, v209, 5
	s_waitcnt lgkmcnt(0)
	v_readfirstlane_b32 s15, v0
	s_cmp_gt_i32 s15, s0
	s_cselect_b32 s10, s10, s11
	s_lshl_b32 s15, s10, 2
	s_add_i32 s15, s15, 0x13008
	v_mov_b32_e32 v0, s15
	ds_read_b32 v0, v0
	s_add_i32 s11, s10, 2
	v_readlane_b32 s50, v209, 6
	v_readlane_b32 s51, v209, 7
	s_waitcnt lgkmcnt(0)
	v_readfirstlane_b32 s15, v0
	s_cmp_gt_i32 s15, s0
	s_cselect_b32 s10, s10, s11
	s_lshl_b32 s15, s10, 2
	s_add_i32 s15, s15, 0x13004
	v_mov_b32_e32 v0, s15
	ds_read_b32 v0, v0
	s_add_i32 s11, s10, 1
	s_waitcnt lgkmcnt(0)
	v_readfirstlane_b32 s15, v0
	s_cmp_gt_i32 s15, s0
	s_cselect_b32 s16, s10, s11
	s_lshl_b32 s10, s16, 2
	s_add_i32 s10, s10, 0x13000
	v_mov_b32_e32 v0, s10
	ds_read_b32 v2, v0
	s_lshl_b64 s[10:11], s[16:17], 16
	s_add_u32 s10, s56, s10
	s_addc_u32 s11, s57, s11
	s_waitcnt lgkmcnt(0)
	v_sub_u32_e32 v2, s0, v2
	v_lshlrev_b32_e32 v2, 7, v2
	v_ashrrev_i32_e32 v3, 31, v2
	v_lshlrev_b64 v[4:5], 2, v[2:3]
	v_and_b32_e32 v3, 8, v118
	v_cmp_eq_u32_e32 vcc, 0, v3
	v_mov_b32_e32 v3, s47
	v_lshl_add_u64 v[4:5], s[10:11], 0, v[4:5]
	v_cndmask_b32_e32 v23, v3, v6, vcc
	v_mov_b32_e32 v3, s46
	v_mov_b32_e32 v6, s44
	v_cndmask_b32_e32 v22, v3, v6, vcc
	v_ashrrev_i32_e32 v6, 3, v118
	v_ashrrev_i32_e32 v7, 31, v6
	v_lshl_add_u64 v[4:5], v[6:7], 2, v[4:5]
	global_load_dword v3, v[4:5], off
	global_load_dword v8, v[4:5], off offset:256
	v_add_u32_e32 v10, v6, v2
	global_load_dword v6, v[4:5], off offset:128
	ds_read_b32 v0, v0 offset:260
	global_load_dword v4, v[4:5], off offset:384
	v_add_u32_e32 v7, 32, v10
	s_add_i32 s10, s16, s8
	v_add_u32_e32 v9, 64, v10
	s_waitcnt lgkmcnt(0)
	v_cmp_lt_i32_e32 vcc, v10, v0
	s_ashr_i32 s11, s10, 31
	s_lshl_b32 s15, s14, 3
	v_add_u32_e32 v5, 0x60, v10
	s_lshl_b64 s[10:11], s[10:11], 20
	s_and_b32 s15, s15, 0xc0
	v_lshl_add_u64 v[10:11], v[22:23], 0, s[10:11]
	s_lshl_b32 s10, s15, 2
	s_mov_b32 s11, s17
	v_lshl_add_u64 v[10:11], v[10:11], 0, s[10:11]
	s_movk_i32 s11, 0x4000
	s_waitcnt vmcnt(3)
	v_ashrrev_i32_e32 v2, 1, v3
	v_cndmask_b32_e32 v2, 0, v2, vcc
	v_cmp_lt_i32_e32 vcc, v7, v0
	s_waitcnt vmcnt(1)
	v_ashrrev_i32_e32 v6, 1, v6
	v_ashrrev_i32_e32 v8, 1, v8
	v_cndmask_b32_e32 v6, 0, v6, vcc
	v_cmp_lt_i32_e32 vcc, v9, v0
	v_ashrrev_i32_e32 v3, 31, v2
	v_lshlrev_b64 v[28:29], 11, v[2:3]
	v_cndmask_b32_e32 v8, 0, v8, vcc
	v_cmp_lt_i32_e32 vcc, v5, v0
	s_waitcnt vmcnt(0)
	v_ashrrev_i32_e32 v0, 1, v4
	v_lshl_add_u64 v[2:3], s[4:5], 0, v[28:29]
	v_cndmask_b32_e32 v4, 0, v0, vcc
	v_lshlrev_b32_e32 v0, 3, v118
	v_and_b32_e32 v24, 0x80, v0
	v_lshl_add_u64 v[10:11], v[10:11], 0, v[24:25]
	v_mov_b32_e32 v25, v144
	v_lshlrev_b32_e32 v0, 4, v118
	v_and_b32_e32 v0, 0x70, v0
	v_ashrrev_i32_e32 v36, 5, v25
	v_ashrrev_i32_e32 v37, 31, v36
	v_lshl_add_u64 v[10:11], v[10:11], 0, v[0:1]
	v_lshlrev_b64 v[26:27], 10, v[36:37]
	v_lshlrev_b32_e32 v0, 4, v25
	v_ashrrev_i32_e32 v7, 31, v6
	v_lshl_add_u64 v[90:91], v[10:11], 0, v[26:27]
	v_and_b32_e32 v0, 0x70, v0
	v_lshlrev_b64 v[30:31], 11, v[6:7]
	v_lshl_add_u64 v[82:83], v[2:3], 0, v[0:1]
	v_add_co_u32_e32 v2, vcc, s93, v90
	v_lshl_add_u64 v[6:7], s[4:5], 0, v[30:31]
	s_nop 0
	v_addc_co_u32_e32 v3, vcc, 0, v91, vcc
	v_lshl_add_u64 v[84:85], v[6:7], 0, v[0:1]
	v_add_co_u32_e32 v6, vcc, s11, v90
	s_movk_i32 s11, 0x6000
	s_nop 0
	v_addc_co_u32_e32 v7, vcc, 0, v91, vcc
	v_add_co_u32_e32 v10, vcc, s11, v90
	v_ashrrev_i32_e32 v5, 31, v4
	s_nop 0
	v_addc_co_u32_e32 v11, vcc, 0, v91, vcc
	v_add_co_u32_e32 v14, vcc, s72, v90
	v_ashrrev_i32_e32 v9, 31, v8
	v_lshlrev_b64 v[34:35], 11, v[4:5]
	global_load_dwordx4 v[18:21], v[90:91], off
	v_addc_co_u32_e32 v15, vcc, 0, v91, vcc
	s_mov_b32 s11, 0xa000
	v_lshlrev_b64 v[32:33], 11, v[8:9]
	v_lshl_add_u64 v[4:5], s[4:5], 0, v[34:35]
	v_add_co_u32_e32 v38, vcc, s11, v90
	v_lshl_add_u64 v[8:9], s[4:5], 0, v[32:33]
	v_lshl_add_u64 v[88:89], v[4:5], 0, v[0:1]
	global_load_dwordx4 v[2:5], v[2:3], off
	v_addc_co_u32_e32 v39, vcc, 0, v91, vcc
	s_mov_b32 s11, 0xc000
	v_lshl_add_u64 v[86:87], v[8:9], 0, v[0:1]
	global_load_dwordx4 v[6:9], v[6:7], off
	v_add_co_u32_e32 v42, vcc, s11, v90
	global_load_dwordx4 v[10:13], v[10:11], off
	s_nop 0
	v_addc_co_u32_e32 v43, vcc, 0, v91, vcc
	global_load_dwordx4 v[14:17], v[14:15], off
	s_mov_b32 s11, 0xe000
	global_load_dwordx4 v[38:41], v[38:39], off
	v_add_co_u32_e32 v46, vcc, s11, v90
	global_load_dwordx4 v[42:45], v[42:43], off
	s_nop 0
	v_addc_co_u32_e32 v47, vcc, 0, v91, vcc
	global_load_dwordx4 v[46:49], v[46:47], off
	s_nop 0
	global_load_dwordx4 v[50:53], v[82:83], off
	global_load_dwordx4 v[54:57], v[84:85], off
	global_load_dwordx4 v[58:61], v[86:87], off
	global_load_dwordx4 v[62:65], v[88:89], off
	v_lshlrev_b32_e32 v66, 2, v25
	v_and_b32_e32 v67, 0x7c, v66
	v_lshl_add_u64 v[92:93], v[90:91], 0, s[38:39]
	s_mov_b64 s[38:39], 0x4000
	v_lshl_add_u64 v[94:95], v[90:91], 0, s[38:39]
	s_mov_b64 s[38:39], 0x6000
	v_lshl_add_u64 v[96:97], v[90:91], 0, s[38:39]
	s_mov_b64 s[38:39], 0x8000
	v_lshl_add_u64 v[98:99], v[90:91], 0, s[38:39]
	s_mov_b64 s[38:39], 0xa000
	v_lshl_add_u64 v[100:101], v[90:91], 0, s[38:39]
	s_mov_b64 s[38:39], 0xc000
	v_lshrrev_b32_e32 v37, 3, v25
	v_lshl_add_u64 v[104:105], v[90:91], 0, s[38:39]
	s_mov_b64 s[38:39], 0xe000
	s_movk_i32 s11, 0x90
	v_readfirstlane_b32 s10, v25
	v_lshl_add_u64 v[106:107], v[90:91], 0, s[38:39]
	v_mad_u64_u32 v[102:103], s[38:39], v37, s11, v[0:1]
	v_and_b32_e32 v0, 31, v25
	v_and_or_b32 v0, s10, 64, v0
	v_lshlrev_b32_e32 v68, 3, v25
	s_ashr_i32 s10, s10, 1
	s_andn2_b32 s10, s10, 63
	s_waitcnt vmcnt(11)
	v_cvt_pk_bf16_f32 v18, v18, v19
	v_cvt_pk_bf16_f32 v19, v20, v21
	v_lshlrev_b32_e32 v20, 7, v36
	v_and_b32_e32 v21, 0x60, v25
	v_bitop3_b32 v120, v67, v20, v21 bitop3:0xde
	v_lshlrev_b32_e32 v119, 1, v120
	s_waitcnt vmcnt(10)
	v_cvt_pk_bf16_f32 v2, v2, v3
	v_cvt_pk_bf16_f32 v3, v4, v5
	ds_write2st64_b64 v119, v[18:19], v[2:3] offset1:4
	s_waitcnt vmcnt(9)
	v_cvt_pk_bf16_f32 v2, v6, v7
	v_cvt_pk_bf16_f32 v3, v8, v9
	s_waitcnt vmcnt(8)
	v_cvt_pk_bf16_f32 v4, v10, v11
	v_cvt_pk_bf16_f32 v5, v12, v13
	ds_write2st64_b64 v119, v[2:3], v[4:5] offset0:8 offset1:12
	s_waitcnt vmcnt(7)
	v_cvt_pk_bf16_f32 v2, v14, v15
	v_cvt_pk_bf16_f32 v3, v16, v17
	s_waitcnt vmcnt(6)
	v_cvt_pk_bf16_f32 v4, v38, v39
	v_cvt_pk_bf16_f32 v5, v40, v41
	ds_write2st64_b64 v119, v[2:3], v[4:5] offset0:16 offset1:20
	s_waitcnt vmcnt(5)
	v_cvt_pk_bf16_f32 v2, v42, v43
	v_cvt_pk_bf16_f32 v3, v44, v45
	s_waitcnt vmcnt(4)
	v_cvt_pk_bf16_f32 v4, v46, v47
	v_cvt_pk_bf16_f32 v5, v48, v49
	ds_write2st64_b64 v119, v[2:3], v[4:5] offset0:24 offset1:28
	v_lshrrev_b32_e32 v2, 1, v25
	v_and_b32_e32 v2, 16, v2
	v_mad_u32_u24 v103, v0, s11, v2
	v_and_b32_e32 v0, 16, v25
	v_and_or_b32 v0, v66, 12, v0
	v_and_b32_e32 v3, 0x60, v68
	v_or_b32_e32 v2, s10, v0
	v_bitop3_b32 v122, v0, v3, s10 bitop3:0x36
	v_readlane_b32 s10, v207, 19
	v_readlane_b32 s11, v207, 20
	v_bitop3_b32 v121, v2, v3, 32 bitop3:0x36
	v_and_b32_e32 v5, 7, v118
	v_lshl_add_u64 v[108:109], s[10:11], 0, v[28:29]
	v_lshl_add_u64 v[110:111], s[10:11], 0, v[30:31]
	v_lshl_add_u64 v[112:113], s[10:11], 0, v[32:33]
	v_lshl_add_u64 v[114:115], s[10:11], 0, v[34:35]
	v_readlane_b32 s10, v207, 25
	s_add_i32 s10, s10, s16
	s_ashr_i32 s11, s10, 31
	s_lshl_b64 s[10:11], s[10:11], 20
	v_lshl_add_u64 v[2:3], s[10:11], 0, v[26:27]
	v_or_b32_e32 v2, s34, v2
	v_lshlrev_b32_e32 v5, 4, v5
	v_lshlrev_b32_e32 v0, 5, v25
	v_or3_b32 v2, v2, v24, v5
	v_and_b32_e32 v4, 0x580, v0
	v_and_b32_e32 v0, 7, v25
	v_lshl_add_u64 v[116:117], v[22:23], 0, v[2:3]
	v_mov_b32_e32 v2, 0
	s_waitcnt vmcnt(3)
	ds_write_b128 v102, v[50:53] offset:32768
	s_waitcnt vmcnt(2)
	ds_write_b128 v102, v[54:57] offset:37376
	s_waitcnt vmcnt(1)
	ds_write_b128 v102, v[58:61] offset:41984
	s_waitcnt vmcnt(0)
	ds_write_b128 v102, v[62:65] offset:46592
	v_lshlrev_b32_e32 v0, 4, v0
	s_mov_b64 s[10:11], 0
	v_lshlrev_b32_e32 v123, 1, v4
	v_mov_b32_e32 v3, v2
	v_mov_b32_e32 v4, v2
	v_mov_b32_e32 v5, v2
	v_mov_b32_e32 v6, v2
	v_mov_b32_e32 v7, v2
	v_mov_b32_e32 v8, v2
	v_mov_b32_e32 v9, v2
	v_mov_b32_e32 v10, v2
	v_mov_b32_e32 v11, v2
	v_mov_b32_e32 v12, v2
	v_mov_b32_e32 v13, v2
	v_mov_b32_e32 v14, v2
	v_mov_b32_e32 v15, v2
	v_mov_b32_e32 v16, v2
	v_mov_b32_e32 v17, v2
	v_mov_b32_e32 v34, v2
	v_mov_b32_e32 v35, v2
	v_mov_b32_e32 v36, v2
	v_mov_b32_e32 v37, v2
	v_mov_b32_e32 v38, v2
	v_mov_b32_e32 v39, v2
	v_mov_b32_e32 v40, v2
	v_mov_b32_e32 v41, v2
	v_mov_b32_e32 v42, v2
	v_mov_b32_e32 v43, v2
	v_mov_b32_e32 v44, v2
	v_mov_b32_e32 v45, v2
	v_mov_b32_e32 v46, v2
	v_mov_b32_e32 v47, v2
	v_mov_b32_e32 v48, v2
	v_mov_b32_e32 v49, v2
	v_mov_b32_e32 v18, v2
	v_mov_b32_e32 v19, v2
	v_mov_b32_e32 v20, v2
	v_mov_b32_e32 v21, v2
	v_mov_b32_e32 v22, v2
	v_mov_b32_e32 v23, v2
	v_mov_b32_e32 v24, v2
	v_mov_b32_e32 v25, v2
	v_mov_b32_e32 v26, v2
	v_mov_b32_e32 v27, v2
	v_mov_b32_e32 v28, v2
	v_mov_b32_e32 v29, v2
	v_mov_b32_e32 v30, v2
	v_mov_b32_e32 v31, v2
	v_mov_b32_e32 v32, v2
	v_mov_b32_e32 v33, v2
	v_mov_b32_e32 v50, v2
	v_mov_b32_e32 v51, v2
	v_mov_b32_e32 v52, v2
	v_mov_b32_e32 v53, v2
	v_mov_b32_e32 v54, v2
	v_mov_b32_e32 v55, v2
	v_mov_b32_e32 v56, v2
	v_mov_b32_e32 v57, v2
	v_mov_b32_e32 v58, v2
	v_mov_b32_e32 v59, v2
	v_mov_b32_e32 v60, v2
	v_mov_b32_e32 v61, v2
	v_mov_b32_e32 v62, v2
	v_mov_b32_e32 v63, v2
	v_mov_b32_e32 v64, v2
	v_mov_b32_e32 v65, v2
	s_waitcnt lgkmcnt(0)
	s_barrier

.LBB0_899:
	s_ashr_i32 s1, s12, 6
	s_and_b32 s0, s12, 7
	s_and_b32 s1, s1, 0x1ffffff8
	s_or_b32 s0, s1, s0
	s_lshl_b32 s0, s0, 3
	s_bfe_u32 s1, s12, 0x30006
	s_or_b32 s0, s0, s1
	s_cmpk_lt_i32 s12, 0x800
	s_cbranch_scc1 .Lp8b_eb_ok
	s_bfe_u32 s1, s12, 0x30006
	s_lshl_b32 s1, s1, 3
	s_and_b32 s0, s12, 7
	s_or_b32 s0, s0, s1
	s_addk_i32 s0, 0x100
.Lp8b_eb_ok:
	s_cmp_ge_i32 s0, s9
	s_cbranch_scc1 .LBB0_898
	ds_read_b32 v0, v169
	v_mov_b32_e32 v115, v144
	v_readlane_b32 s34, v208, 46
	v_readlane_b32 s35, v208, 47
	v_readlane_b32 s44, v209, 0
	s_waitcnt lgkmcnt(0)
	v_readfirstlane_b32 s1, v0
	s_cmp_gt_i32 s1, s0
	s_cselect_b32 s1, 0, 32
	s_lshl_b32 s14, s1, 2
	s_or_b32 s14, s14, 0x13040
	v_mov_b32_e32 v0, s14
	ds_read_b32 v0, v0
	s_or_b32 s13, s1, 16
	v_readlane_b32 s48, v209, 4
	v_readlane_b32 s49, v209, 5
	v_mov_b32_e32 v32, v144
	s_waitcnt lgkmcnt(0)
	v_readfirstlane_b32 s14, v0
	s_cmp_gt_i32 s14, s0
	s_cselect_b32 s1, s1, s13
	s_lshl_b32 s14, s1, 2
	s_or_b32 s14, s14, 0x13020
	v_mov_b32_e32 v0, s14
	ds_read_b32 v0, v0
	s_or_b32 s13, s1, 8
	v_readlane_b32 s45, v209, 1
	v_readlane_b32 s46, v209, 2
	v_readlane_b32 s47, v209, 3
	s_waitcnt lgkmcnt(0)
	v_readfirstlane_b32 s14, v0
	s_cmp_gt_i32 s14, s0
	s_cselect_b32 s1, s1, s13
	s_lshl_b32 s14, s1, 2
	s_or_b32 s14, s14, 0x13010
	v_mov_b32_e32 v0, s14
	ds_read_b32 v0, v0
	s_or_b32 s13, s1, 4
	v_readlane_b32 s50, v209, 6
	v_readlane_b32 s51, v209, 7
	s_waitcnt lgkmcnt(0)
	v_readfirstlane_b32 s14, v0
	s_cmp_gt_i32 s14, s0
	s_cselect_b32 s1, s1, s13
	s_lshl_b32 s14, s1, 2
	s_add_i32 s14, s14, 0x13008
	v_mov_b32_e32 v0, s14
	ds_read_b32 v0, v0
	s_add_i32 s13, s1, 2
	s_waitcnt lgkmcnt(0)
	v_readfirstlane_b32 s14, v0
	s_cmp_gt_i32 s14, s0
	s_cselect_b32 s1, s1, s13
	s_lshl_b32 s14, s1, 2
	s_add_i32 s14, s14, 0x13004
	v_mov_b32_e32 v0, s14
	ds_read_b32 v0, v0
	s_add_i32 s13, s1, 1
	s_waitcnt lgkmcnt(0)
	v_readfirstlane_b32 s14, v0
	s_cmp_gt_i32 s14, s0
	s_cselect_b32 s16, s1, s13
	s_lshl_b32 s1, s16, 2
	s_add_i32 s1, s1, 0x13000
	v_mov_b32_e32 v0, s1
	ds_read_b32 v2, v0
	s_lshl_b64 s[14:15], s[16:17], 16
	s_add_u32 s14, s56, s14
	s_addc_u32 s15, s57, s15
	s_waitcnt lgkmcnt(0)
	v_sub_u32_e32 v2, s0, v2
	v_lshlrev_b32_e32 v2, 7, v2
	v_ashrrev_i32_e32 v3, 31, v2
	v_readfirstlane_b32 s13, v115
	v_and_b32_e32 v6, 31, v115
	v_lshlrev_b64 v[4:5], 2, v[2:3]
	ds_read_b32 v7, v0 offset:260
	v_lshl_add_u64 v[4:5], s[14:15], 0, v[4:5]
	v_and_or_b32 v0, s13, 64, v6
	v_lshlrev_b32_e32 v6, 2, v0
	v_readfirstlane_b32 s14, v4
	v_readfirstlane_b32 s15, v5
	v_or_b32_e32 v4, v0, v2
	s_waitcnt lgkmcnt(0)
	v_cmp_lt_i32_e32 vcc, v4, v7
	s_ashr_i32 s1, s0, 31
	s_lshl_b64 s[0:1], s[0:1], 16
	global_load_dword v3, v6, s[14:15]
	s_waitcnt vmcnt(0)
	v_cndmask_b32_e32 v120, -1, v3, vcc
	v_max_i32_e32 v0, 0, v120
	v_lshl_add_u64 v[2:3], v[0:1], 2, s[34:35]
	global_load_dword v116, v[2:3], off
	global_load_dword v0, v6, s[14:15] offset:128
	v_or_b32_e32 v2, 32, v4
	v_cmp_lt_i32_e32 vcc, v2, v7
	s_add_i32 s14, s16, s8
	s_ashr_i32 s15, s14, 31
	s_waitcnt vmcnt(0)
	v_cndmask_b32_e32 v118, -1, v0, vcc
	v_max_i32_e32 v0, 0, v118
	v_lshl_add_u64 v[2:3], v[0:1], 2, s[34:35]
	global_load_dword v114, v[2:3], off
	s_lshl_b64 s[34:35], s[14:15], 20
	s_and_b32 s14, s11, 0x380
	v_ashrrev_i32_e32 v2, 3, v115
	s_add_u32 s0, s78, s0
	v_ashrrev_i32_e32 v3, 31, v2
	s_addc_u32 s1, s79, s1
	v_lshlrev_b64 v[2:3], 9, v[2:3]
	v_lshl_add_u64 v[2:3], s[0:1], 0, v[2:3]
	s_add_u32 s0, s48, s34
	s_addc_u32 s1, s49, s35
	s_lshl_b32 s15, s14, 2
	s_add_u32 s0, s0, s15
	v_lshlrev_b32_e32 v0, 4, v115
	s_addc_u32 s1, s1, 0
	v_ashrrev_i32_e32 v30, 5, v32
	v_and_b32_e32 v0, 0x1f0, v0
	v_ashrrev_i32_e32 v31, 31, v30
	v_lshl_add_u64 v[4:5], s[0:1], 0, v[0:1]
	v_lshlrev_b64 v[6:7], 12, v[30:31]
	v_lshl_add_u64 v[124:125], v[4:5], 0, v[6:7]
	v_add_co_u32_e32 v126, vcc, s72, v124
	global_load_dwordx4 v[18:21], v[124:125], off
	s_nop 0
	v_addc_co_u32_e32 v127, vcc, 0, v125, vcc
	v_add_co_u32_e32 v128, vcc, s33, v124
	s_mov_b32 s1, 0x28000
	s_nop 0
	v_addc_co_u32_e32 v129, vcc, 0, v125, vcc
	v_add_co_u32_e32 v130, vcc, s36, v124
	v_lshlrev_b32_e32 v0, 4, v32
	s_nop 0
	v_addc_co_u32_e32 v131, vcc, 0, v125, vcc
	v_add_co_u32_e32 v132, vcc, s87, v124
	v_and_b32_e32 v0, 0x70, v0
	s_nop 0
	v_addc_co_u32_e32 v133, vcc, 0, v125, vcc
	v_add_co_u32_e32 v134, vcc, s1, v124
	s_mov_b32 s1, 0x30000
	s_nop 0
	v_addc_co_u32_e32 v135, vcc, 0, v125, vcc
	v_lshl_add_u64 v[122:123], v[2:3], 0, v[0:1]
	global_load_dwordx4 v[2:5], v[126:127], off
	v_add_co_u32_e32 v136, vcc, s1, v124
	global_load_dwordx4 v[6:9], v[128:129], off
	global_load_dwordx4 v[10:13], v[130:131], off
	v_addc_co_u32_e32 v137, vcc, 0, v125, vcc
	s_mov_b32 s1, 0x38000
	global_load_dwordx4 v[14:17], v[132:133], off
	global_load_dwordx4 v[22:25], v[134:135], off
	v_add_co_u32_e32 v138, vcc, s1, v124
	global_load_dwordx4 v[26:29], v[136:137], off
	s_nop 0
	v_addc_co_u32_e32 v139, vcc, 0, v125, vcc
	global_load_dwordx4 v[34:37], v[138:139], off
	global_load_dwordx4 v[38:41], v[122:123], off
	s_movk_i32 s1, 0x4000
	v_add_co_u32_e32 v154, vcc, s1, v122
	s_mov_b32 s1, 0xc000
	s_nop 0
	v_addc_co_u32_e32 v155, vcc, 0, v123, vcc
	v_add_co_u32_e32 v156, vcc, s72, v122
	global_load_dwordx4 v[42:45], v[154:155], off
	s_nop 0
	v_addc_co_u32_e32 v157, vcc, 0, v123, vcc
	v_add_co_u32_e32 v158, vcc, s1, v122
	global_load_dwordx4 v[46:49], v[156:157], off
	s_nop 0
	v_addc_co_u32_e32 v159, vcc, 0, v123, vcc
	global_load_dwordx4 v[50:53], v[158:159], off
	v_lshlrev_b32_e32 v33, 2, v32
	s_movk_i32 s1, 0x7c
	s_mov_b64 s[34:35], 0x4000
	v_lshl_add_u64 v[142:143], v[122:123], 0, s[34:35]
	s_mov_b64 s[34:35], 0x8000
	v_lshrrev_b32_e32 v31, 3, v32
	v_lshl_add_u64 v[150:151], v[122:123], 0, s[34:35]
	s_mov_b64 s[34:35], 0xc000
	v_readfirstlane_b32 s0, v32
	v_lshl_add_u64 v[152:153], v[122:123], 0, s[34:35]
	v_lshlrev_b32_e32 v54, 3, v32
	s_waitcnt vmcnt(11)
	v_cvt_pk_bf16_f32 v18, v18, v19
	v_cvt_pk_bf16_f32 v19, v20, v21
	v_and_b32_e32 v20, 0x60, v32
	v_bitop3_b32 v20, v33, v20, s1 bitop3:0x6c
	v_lshlrev_b32_e32 v20, 1, v20
	v_lshl_or_b32 v117, v30, 8, v20
	s_movk_i32 s1, 0x90
	v_mad_u64_u32 v[140:141], s[34:35], v31, s1, v[0:1]
	v_and_b32_e32 v0, 31, v32
	v_and_or_b32 v0, s0, 64, v0
	s_ashr_i32 s0, s0, 1
	s_andn2_b32 s0, s0, 63
	s_waitcnt vmcnt(10)
	v_cvt_pk_bf16_f32 v2, v2, v3
	v_cvt_pk_bf16_f32 v3, v4, v5
	ds_write2st64_b64 v117, v[18:19], v[2:3] offset1:4
	s_waitcnt vmcnt(9)
	v_cvt_pk_bf16_f32 v2, v6, v7
	v_cvt_pk_bf16_f32 v3, v8, v9
	s_waitcnt vmcnt(8)
	v_cvt_pk_bf16_f32 v4, v10, v11
	v_cvt_pk_bf16_f32 v5, v12, v13
	ds_write2st64_b64 v117, v[2:3], v[4:5] offset0:8 offset1:12
	s_waitcnt vmcnt(7)
	v_cvt_pk_bf16_f32 v2, v14, v15
	v_cvt_pk_bf16_f32 v3, v16, v17
	s_waitcnt vmcnt(6)
	v_cvt_pk_bf16_f32 v4, v22, v23
	v_cvt_pk_bf16_f32 v5, v24, v25
	ds_write2st64_b64 v117, v[2:3], v[4:5] offset0:16 offset1:20
	s_waitcnt vmcnt(5)
	v_cvt_pk_bf16_f32 v2, v26, v27
	v_cvt_pk_bf16_f32 v3, v28, v29
	s_waitcnt vmcnt(4)
	v_cvt_pk_bf16_f32 v4, v34, v35
	v_cvt_pk_bf16_f32 v5, v36, v37
	ds_write2st64_b64 v117, v[2:3], v[4:5] offset0:24 offset1:28
	v_lshrrev_b32_e32 v2, 1, v32
	v_and_b32_e32 v2, 16, v2
	v_mad_u32_u24 v0, v0, s1, v2
	v_and_b32_e32 v2, 16, v32
	v_and_or_b32 v2, v33, 12, v2
	v_and_b32_e32 v4, 0x60, v54
	v_or_b32_e32 v3, s0, v2
	v_bitop3_b32 v5, v2, v4, s0 bitop3:0x36
	s_mov_b32 s0, 0x40000
	v_add_co_u32_e32 v2, vcc, s0, v124
	v_bitop3_b32 v14, v3, v4, 32 bitop3:0x36
	s_nop 0
	v_addc_co_u32_e32 v3, vcc, 0, v125, vcc
	s_mov_b32 s0, 0x48000
	s_waitcnt vmcnt(3)
	ds_write_b128 v140, v[38:41] offset:32768
	s_waitcnt vmcnt(2)
	ds_write_b128 v140, v[42:45] offset:37376
	s_waitcnt vmcnt(1)
	ds_write_b128 v140, v[46:49] offset:41984
	s_waitcnt vmcnt(0)
	ds_write_b128 v140, v[50:53] offset:46592
	s_waitcnt lgkmcnt(0)
	s_barrier
	global_load_dwordx4 v[66:69], v[2:3], off
	v_add_co_u32_e32 v2, vcc, s0, v124
	s_mov_b32 s0, 0x50000
	s_nop 0
	v_addc_co_u32_e32 v3, vcc, 0, v125, vcc
	global_load_dwordx4 v[70:73], v[2:3], off
	v_add_co_u32_e32 v2, vcc, s0, v124
	s_mov_b32 s0, 0x58000
	s_nop 0
	v_addc_co_u32_e32 v3, vcc, 0, v125, vcc
	global_load_dwordx4 v[74:77], v[2:3], off
	v_add_co_u32_e32 v2, vcc, s0, v124
	s_mov_b32 s0, 0x60000
	s_nop 0
	v_addc_co_u32_e32 v3, vcc, 0, v125, vcc
	global_load_dwordx4 v[78:81], v[2:3], off
	v_add_co_u32_e32 v2, vcc, s0, v124
	s_mov_b32 s0, 0x68000
	s_nop 0
	v_addc_co_u32_e32 v3, vcc, 0, v125, vcc
	global_load_dwordx4 v[82:85], v[2:3], off
	v_add_co_u32_e32 v2, vcc, s0, v124
	s_mov_b32 s0, 0x70000
	s_nop 0
	v_addc_co_u32_e32 v3, vcc, 0, v125, vcc
	global_load_dwordx4 v[86:89], v[2:3], off
	v_add_co_u32_e32 v2, vcc, s0, v124
	s_mov_b32 s0, 0x78000
	s_nop 0
	v_addc_co_u32_e32 v3, vcc, 0, v125, vcc
	global_load_dwordx4 v[90:93], v[2:3], off
	v_add_co_u32_e32 v2, vcc, s0, v124
	s_nop 1
	v_addc_co_u32_e32 v3, vcc, 0, v125, vcc
	global_load_dwordx4 v[110:113], v[2:3], off
	global_load_dwordx4 v[94:97], v[122:123], off offset:128
	global_load_dwordx4 v[98:101], v[142:143], off offset:128
	global_load_dwordx4 v[102:105], v[150:151], off offset:128
	global_load_dwordx4 v[106:109], v[152:153], off offset:128
	v_lshlrev_b32_e32 v2, 6, v32
	v_and_b32_e32 v15, 0xb00, v2
	v_lshl_add_u32 v121, v5, 1, v15
	v_lshl_add_u32 v119, v14, 1, v15
	ds_read_b64_tr_b16 v[2:3], v121
	ds_read_b64_tr_b16 v[4:5], v121 offset:1024
	ds_read_b128 v[6:9], v0 offset:32768
	ds_read_b128 v[10:13], v0 offset:37376
	ds_read_b64_tr_b16 v[14:15], v119
	ds_read_b64_tr_b16 v[16:17], v119 offset:1024
	ds_read_b64_tr_b16 v[186:187], v121 offset:4096
	ds_read_b64_tr_b16 v[188:189], v121 offset:5120
	ds_read_b128 v[190:193], v0 offset:32800
	ds_read_b128 v[194:197], v0 offset:37408
	ds_read_b64_tr_b16 v[198:199], v119 offset:4096
	ds_read_b64_tr_b16 v[200:201], v119 offset:5120
	s_waitcnt lgkmcnt(9)
	v_mfma_f32_32x32x16_bf16 v[50:65], v[2:5], v[6:9], 0
	s_waitcnt lgkmcnt(8)
	v_mfma_f32_32x32x16_bf16 v[18:33], v[2:5], v[10:13], 0
	s_waitcnt lgkmcnt(6)
	v_mfma_f32_32x32x16_bf16 v[34:49], v[14:17], v[6:9], 0
	v_mfma_f32_32x32x16_bf16 v[2:17], v[14:17], v[10:13], 0
	s_waitcnt lgkmcnt(3)
	v_mfma_f32_32x32x16_bf16 v[50:65], v[186:189], v[190:193], v[50:65]
	s_waitcnt lgkmcnt(2)
	v_mfma_f32_32x32x16_bf16 v[18:33], v[186:189], v[194:197], v[18:33]
	s_waitcnt lgkmcnt(0)
	v_mfma_f32_32x32x16_bf16 v[34:49], v[198:201], v[190:193], v[34:49]
	ds_read_b64_tr_b16 v[186:187], v121 offset:8192
	ds_read_b64_tr_b16 v[188:189], v121 offset:9216
	ds_read_b128 v[190:193], v0 offset:32832
	v_mfma_f32_32x32x16_bf16 v[2:17], v[198:201], v[194:197], v[2:17]
	ds_read_b128 v[194:197], v0 offset:37440
	ds_read_b64_tr_b16 v[198:199], v119 offset:8192
	ds_read_b64_tr_b16 v[200:201], v119 offset:9216
	s_waitcnt lgkmcnt(3)
	v_mfma_f32_32x32x16_bf16 v[50:65], v[186:189], v[190:193], v[50:65]
	s_waitcnt lgkmcnt(2)
	v_mfma_f32_32x32x16_bf16 v[18:33], v[186:189], v[194:197], v[18:33]
	s_waitcnt lgkmcnt(0)
	v_mfma_f32_32x32x16_bf16 v[34:49], v[198:201], v[190:193], v[34:49]
	ds_read_b64_tr_b16 v[186:187], v121 offset:12288
	ds_read_b64_tr_b16 v[188:189], v121 offset:13312
	ds_read_b128 v[190:193], v0 offset:32864
	v_mfma_f32_32x32x16_bf16 v[2:17], v[198:201], v[194:197], v[2:17]
	ds_read_b128 v[194:197], v0 offset:37472
	ds_read_b64_tr_b16 v[198:199], v119 offset:12288
	ds_read_b64_tr_b16 v[200:201], v119 offset:13312
	s_waitcnt lgkmcnt(3)
	v_mfma_f32_32x32x16_bf16 v[50:65], v[186:189], v[190:193], v[50:65]
	s_waitcnt lgkmcnt(2)
	v_mfma_f32_32x32x16_bf16 v[18:33], v[186:189], v[194:197], v[18:33]
	s_waitcnt lgkmcnt(0)
	v_mfma_f32_32x32x16_bf16 v[34:49], v[198:201], v[190:193], v[34:49]
	v_mfma_f32_32x32x16_bf16 v[2:17], v[198:201], v[194:197], v[2:17]
	s_waitcnt vmcnt(11)
	v_cvt_pk_bf16_f32 v66, v66, v67
	v_cvt_pk_bf16_f32 v67, v68, v69
	s_waitcnt vmcnt(10)
	v_cvt_pk_bf16_f32 v68, v70, v71
	v_cvt_pk_bf16_f32 v69, v72, v73
	ds_write2st64_b64 v117, v[66:67], v[68:69] offset0:32 offset1:36
	s_waitcnt vmcnt(9)
	v_cvt_pk_bf16_f32 v66, v74, v75
	v_cvt_pk_bf16_f32 v67, v76, v77
	s_waitcnt vmcnt(8)
	v_cvt_pk_bf16_f32 v68, v78, v79
	v_cvt_pk_bf16_f32 v69, v80, v81
	ds_write2st64_b64 v117, v[66:67], v[68:69] offset0:40 offset1:44
	s_waitcnt vmcnt(7)
	v_cvt_pk_bf16_f32 v66, v82, v83
	v_cvt_pk_bf16_f32 v67, v84, v85
	s_waitcnt vmcnt(6)
	v_cvt_pk_bf16_f32 v68, v86, v87
	v_cvt_pk_bf16_f32 v69, v88, v89
	ds_write2st64_b64 v117, v[66:67], v[68:69] offset0:48 offset1:52
	s_waitcnt vmcnt(5)
	v_cvt_pk_bf16_f32 v66, v90, v91
	v_cvt_pk_bf16_f32 v67, v92, v93
	s_waitcnt vmcnt(4)
	v_cvt_pk_bf16_f32 v68, v110, v111
	v_cvt_pk_bf16_f32 v69, v112, v113
	s_mov_b32 s0, 0x80000
	ds_write2st64_b64 v117, v[66:67], v[68:69] offset0:56 offset1:60
	s_waitcnt vmcnt(3)
	ds_write_b128 v140, v[94:97] offset:51200
	s_waitcnt vmcnt(2)
	ds_write_b128 v140, v[98:101] offset:55808
	s_waitcnt vmcnt(1)
	ds_write_b128 v140, v[102:105] offset:60416
	s_waitcnt vmcnt(0)
	ds_write_b128 v140, v[106:109] offset:65024
	v_add_co_u32_e32 v66, vcc, s0, v124
	s_mov_b32 s0, 0x88000
	s_nop 0
	v_addc_co_u32_e32 v67, vcc, 0, v125, vcc
	v_add_co_u32_e32 v70, vcc, s0, v124
	s_mov_b32 s0, 0x90000
	s_nop 0
	v_addc_co_u32_e32 v71, vcc, 0, v125, vcc
	v_add_co_u32_e32 v74, vcc, s0, v124
	s_mov_b32 s0, 0x98000
	s_nop 0
	v_addc_co_u32_e32 v75, vcc, 0, v125, vcc
	v_add_co_u32_e32 v78, vcc, s0, v124
	s_mov_b32 s0, 0xa0000
	s_nop 0
	v_addc_co_u32_e32 v79, vcc, 0, v125, vcc
	v_add_co_u32_e32 v82, vcc, s0, v124
	s_mov_b32 s0, 0xa8000
	s_nop 0
	v_addc_co_u32_e32 v83, vcc, 0, v125, vcc
	v_add_co_u32_e32 v86, vcc, s0, v124
	s_mov_b32 s0, 0xb0000
	s_nop 0
	v_addc_co_u32_e32 v87, vcc, 0, v125, vcc
	v_add_co_u32_e32 v90, vcc, s0, v124
	s_mov_b32 s0, 0xb8000
	s_nop 0
	v_addc_co_u32_e32 v91, vcc, 0, v125, vcc
	v_add_co_u32_e32 v94, vcc, s0, v124
	s_waitcnt lgkmcnt(0)
	s_nop 0
	v_addc_co_u32_e32 v95, vcc, 0, v125, vcc
	s_barrier
	global_load_dwordx4 v[66:69], v[66:67], off
	s_nop 0
	global_load_dwordx4 v[70:73], v[70:71], off
	s_nop 0
	global_load_dwordx4 v[74:77], v[74:75], off
	s_nop 0
	global_load_dwordx4 v[78:81], v[78:79], off
	s_nop 0
	global_load_dwordx4 v[82:85], v[82:83], off
	s_nop 0
	global_load_dwordx4 v[86:89], v[86:87], off
	s_nop 0
	global_load_dwordx4 v[90:93], v[90:91], off
	s_nop 0
	global_load_dwordx4 v[94:97], v[94:95], off
	s_nop 0
	global_load_dwordx4 v[98:101], v[122:123], off offset:256
	global_load_dwordx4 v[102:105], v[142:143], off offset:256
	global_load_dwordx4 v[106:109], v[150:151], off offset:256
	global_load_dwordx4 v[110:113], v[152:153], off offset:256
	ds_read_b64_tr_b16 v[186:187], v121 offset:16384
	ds_read_b64_tr_b16 v[188:189], v121 offset:17408
	ds_read_b128 v[190:193], v0 offset:51200
	ds_read_b128 v[194:197], v0 offset:55808
	ds_read_b64_tr_b16 v[198:199], v119 offset:16384
	ds_read_b64_tr_b16 v[200:201], v119 offset:17408
	s_waitcnt lgkmcnt(2)
	v_mfma_f32_32x32x16_bf16 v[18:33], v[186:189], v[194:197], v[18:33]
	v_mfma_f32_32x32x16_bf16 v[50:65], v[186:189], v[190:193], v[50:65]
	s_waitcnt lgkmcnt(0)
	v_mfma_f32_32x32x16_bf16 v[34:49], v[198:201], v[190:193], v[34:49]
	ds_read_b64_tr_b16 v[186:187], v121 offset:20480
	ds_read_b64_tr_b16 v[188:189], v121 offset:21504
	ds_read_b128 v[190:193], v0 offset:51232
	v_mfma_f32_32x32x16_bf16 v[2:17], v[198:201], v[194:197], v[2:17]
	ds_read_b128 v[194:197], v0 offset:55840
	ds_read_b64_tr_b16 v[198:199], v119 offset:20480
	ds_read_b64_tr_b16 v[200:201], v119 offset:21504
	s_waitcnt lgkmcnt(3)
	v_mfma_f32_32x32x16_bf16 v[50:65], v[186:189], v[190:193], v[50:65]
	s_waitcnt lgkmcnt(2)
	v_mfma_f32_32x32x16_bf16 v[18:33], v[186:189], v[194:197], v[18:33]
	s_waitcnt lgkmcnt(0)
	v_mfma_f32_32x32x16_bf16 v[34:49], v[198:201], v[190:193], v[34:49]
	ds_read_b64_tr_b16 v[186:187], v121 offset:24576
	ds_read_b64_tr_b16 v[188:189], v121 offset:25600
	ds_read_b128 v[190:193], v0 offset:51264
	v_mfma_f32_32x32x16_bf16 v[2:17], v[198:201], v[194:197], v[2:17]
	ds_read_b128 v[194:197], v0 offset:55872
	ds_read_b64_tr_b16 v[198:199], v119 offset:24576
	ds_read_b64_tr_b16 v[200:201], v119 offset:25600
	s_waitcnt lgkmcnt(3)
	v_mfma_f32_32x32x16_bf16 v[50:65], v[186:189], v[190:193], v[50:65]
	s_waitcnt lgkmcnt(2)
	v_mfma_f32_32x32x16_bf16 v[18:33], v[186:189], v[194:197], v[18:33]
	s_waitcnt lgkmcnt(0)
	v_mfma_f32_32x32x16_bf16 v[34:49], v[198:201], v[190:193], v[34:49]
	ds_read_b64_tr_b16 v[186:187], v121 offset:28672
	ds_read_b64_tr_b16 v[188:189], v121 offset:29696
	ds_read_b128 v[190:193], v0 offset:51296
	v_mfma_f32_32x32x16_bf16 v[2:17], v[198:201], v[194:197], v[2:17]
	ds_read_b128 v[194:197], v0 offset:55904
	ds_read_b64_tr_b16 v[198:199], v119 offset:28672
	ds_read_b64_tr_b16 v[200:201], v119 offset:29696
	s_waitcnt lgkmcnt(3)
	v_mfma_f32_32x32x16_bf16 v[50:65], v[186:189], v[190:193], v[50:65]
	s_waitcnt lgkmcnt(2)
	v_mfma_f32_32x32x16_bf16 v[18:33], v[186:189], v[194:197], v[18:33]
	s_waitcnt lgkmcnt(0)
	v_mfma_f32_32x32x16_bf16 v[34:49], v[198:201], v[190:193], v[34:49]
	v_mfma_f32_32x32x16_bf16 v[2:17], v[198:201], v[194:197], v[2:17]
	s_waitcnt vmcnt(11)
	v_cvt_pk_bf16_f32 v66, v66, v67
	v_cvt_pk_bf16_f32 v67, v68, v69
	s_waitcnt vmcnt(10)
	v_cvt_pk_bf16_f32 v68, v70, v71
	v_cvt_pk_bf16_f32 v69, v72, v73
	ds_write2st64_b64 v117, v[66:67], v[68:69] offset1:4
	s_waitcnt vmcnt(9)
	v_cvt_pk_bf16_f32 v66, v74, v75
	v_cvt_pk_bf16_f32 v67, v76, v77
	s_waitcnt vmcnt(8)
	v_cvt_pk_bf16_f32 v68, v78, v79
	v_cvt_pk_bf16_f32 v69, v80, v81
	ds_write2st64_b64 v117, v[66:67], v[68:69] offset0:8 offset1:12
	s_waitcnt vmcnt(7)
	v_cvt_pk_bf16_f32 v66, v82, v83
	v_cvt_pk_bf16_f32 v67, v84, v85
	s_waitcnt vmcnt(6)
	v_cvt_pk_bf16_f32 v68, v86, v87
	v_cvt_pk_bf16_f32 v69, v88, v89
	ds_write2st64_b64 v117, v[66:67], v[68:69] offset0:16 offset1:20
	s_waitcnt vmcnt(5)
	v_cvt_pk_bf16_f32 v66, v90, v91
	v_cvt_pk_bf16_f32 v67, v92, v93
	s_waitcnt vmcnt(4)
	v_cvt_pk_bf16_f32 v68, v94, v95
	v_cvt_pk_bf16_f32 v69, v96, v97
	s_mov_b32 s0, 0xc0000
	ds_write2st64_b64 v117, v[66:67], v[68:69] offset0:24 offset1:28
	s_waitcnt vmcnt(3)
	ds_write_b128 v140, v[98:101] offset:32768
	s_waitcnt vmcnt(2)
	ds_write_b128 v140, v[102:105] offset:37376
	s_waitcnt vmcnt(1)
	ds_write_b128 v140, v[106:109] offset:41984
	s_waitcnt vmcnt(0)
	ds_write_b128 v140, v[110:113] offset:46592
	v_add_co_u32_e32 v66, vcc, s0, v124
	s_mov_b32 s0, 0xc8000
	s_nop 0
	v_addc_co_u32_e32 v67, vcc, 0, v125, vcc
	v_add_co_u32_e32 v70, vcc, s0, v124
	s_mov_b32 s0, 0xd0000
	s_nop 0
	v_addc_co_u32_e32 v71, vcc, 0, v125, vcc
	v_add_co_u32_e32 v74, vcc, s0, v124
	s_mov_b32 s0, 0xd8000
	s_nop 0
	v_addc_co_u32_e32 v75, vcc, 0, v125, vcc
	v_add_co_u32_e32 v78, vcc, s0, v124
	s_mov_b32 s0, 0xe0000
	s_nop 0
	v_addc_co_u32_e32 v79, vcc, 0, v125, vcc
	v_add_co_u32_e32 v82, vcc, s0, v124
	s_mov_b32 s0, 0xe8000
	s_nop 0
	v_addc_co_u32_e32 v83, vcc, 0, v125, vcc
	v_add_co_u32_e32 v86, vcc, s0, v124
	s_mov_b32 s0, 0xf0000
	s_nop 0
	v_addc_co_u32_e32 v87, vcc, 0, v125, vcc
	v_add_co_u32_e32 v90, vcc, s0, v124
	s_mov_b32 s0, 0xf8000
	s_nop 0
	v_addc_co_u32_e32 v91, vcc, 0, v125, vcc
	v_add_co_u32_e32 v94, vcc, s0, v124
	s_waitcnt lgkmcnt(0)
	s_nop 0
	v_addc_co_u32_e32 v95, vcc, 0, v125, vcc
	s_barrier
	global_load_dwordx4 v[66:69], v[66:67], off
	s_nop 0
	global_load_dwordx4 v[70:73], v[70:71], off
	s_nop 0
	global_load_dwordx4 v[74:77], v[74:75], off
	s_nop 0
	global_load_dwordx4 v[78:81], v[78:79], off
	s_nop 0
	global_load_dwordx4 v[82:85], v[82:83], off
	s_nop 0
	global_load_dwordx4 v[86:89], v[86:87], off
	s_nop 0
	global_load_dwordx4 v[90:93], v[90:91], off
	s_nop 0
	global_load_dwordx4 v[94:97], v[94:95], off
	s_nop 0
	global_load_dwordx4 v[98:101], v[122:123], off offset:384
	global_load_dwordx4 v[102:105], v[142:143], off offset:384
	global_load_dwordx4 v[106:109], v[150:151], off offset:384
	global_load_dwordx4 v[110:113], v[152:153], off offset:384
	ds_read_b64_tr_b16 v[150:151], v121
	ds_read_b64_tr_b16 v[152:153], v121 offset:1024
	ds_read_b128 v[186:189], v0 offset:32768
	ds_read_b128 v[190:193], v0 offset:37376
	ds_read_b64_tr_b16 v[194:195], v119
	ds_read_b64_tr_b16 v[196:197], v119 offset:1024
	s_waitcnt lgkmcnt(2)
	v_mfma_f32_32x32x16_bf16 v[18:33], v[150:153], v[190:193], v[18:33]
	v_mfma_f32_32x32x16_bf16 v[50:65], v[150:153], v[186:189], v[50:65]
	s_waitcnt lgkmcnt(0)
	v_mfma_f32_32x32x16_bf16 v[34:49], v[194:197], v[186:189], v[34:49]
	ds_read_b64_tr_b16 v[150:151], v121 offset:4096
	ds_read_b64_tr_b16 v[152:153], v121 offset:5120
	ds_read_b128 v[186:189], v0 offset:32800
	v_mfma_f32_32x32x16_bf16 v[2:17], v[194:197], v[190:193], v[2:17]
	ds_read_b128 v[190:193], v0 offset:37408
	ds_read_b64_tr_b16 v[194:195], v119 offset:4096
	ds_read_b64_tr_b16 v[196:197], v119 offset:5120
	s_waitcnt lgkmcnt(3)
	v_mfma_f32_32x32x16_bf16 v[50:65], v[150:153], v[186:189], v[50:65]
	s_waitcnt lgkmcnt(2)
	v_mfma_f32_32x32x16_bf16 v[18:33], v[150:153], v[190:193], v[18:33]
	s_waitcnt lgkmcnt(0)
	v_mfma_f32_32x32x16_bf16 v[34:49], v[194:197], v[186:189], v[34:49]
	ds_read_b64_tr_b16 v[150:151], v121 offset:8192
	ds_read_b64_tr_b16 v[152:153], v121 offset:9216
	ds_read_b128 v[186:189], v0 offset:32832
	v_mfma_f32_32x32x16_bf16 v[2:17], v[194:197], v[190:193], v[2:17]
	ds_read_b128 v[190:193], v0 offset:37440
	ds_read_b64_tr_b16 v[194:195], v119 offset:8192
	ds_read_b64_tr_b16 v[196:197], v119 offset:9216
	s_waitcnt lgkmcnt(3)
	v_mfma_f32_32x32x16_bf16 v[50:65], v[150:153], v[186:189], v[50:65]
	s_waitcnt lgkmcnt(2)
	v_mfma_f32_32x32x16_bf16 v[18:33], v[150:153], v[190:193], v[18:33]
	s_waitcnt lgkmcnt(0)
	v_mfma_f32_32x32x16_bf16 v[34:49], v[194:197], v[186:189], v[34:49]
	ds_read_b64_tr_b16 v[150:151], v121 offset:12288
	ds_read_b64_tr_b16 v[152:153], v121 offset:13312
	ds_read_b128 v[186:189], v0 offset:32864
	v_mfma_f32_32x32x16_bf16 v[2:17], v[194:197], v[190:193], v[2:17]
	ds_read_b128 v[190:193], v0 offset:37472
	ds_read_b64_tr_b16 v[194:195], v119 offset:12288
	ds_read_b64_tr_b16 v[196:197], v119 offset:13312
	s_waitcnt lgkmcnt(3)
	v_mfma_f32_32x32x16_bf16 v[50:65], v[150:153], v[186:189], v[50:65]
	s_waitcnt lgkmcnt(2)
	v_mfma_f32_32x32x16_bf16 v[18:33], v[150:153], v[190:193], v[18:33]
	s_waitcnt lgkmcnt(0)
	v_mfma_f32_32x32x16_bf16 v[34:49], v[194:197], v[186:189], v[34:49]
	v_mfma_f32_32x32x16_bf16 v[2:17], v[194:197], v[190:193], v[2:17]
	s_waitcnt vmcnt(11)
	v_cvt_pk_bf16_f32 v66, v66, v67
	v_cvt_pk_bf16_f32 v67, v68, v69
	s_waitcnt vmcnt(10)
	v_cvt_pk_bf16_f32 v68, v70, v71
	v_cvt_pk_bf16_f32 v69, v72, v73
	ds_write2st64_b64 v117, v[66:67], v[68:69] offset0:32 offset1:36
	s_waitcnt vmcnt(9)
	v_cvt_pk_bf16_f32 v66, v74, v75
	v_cvt_pk_bf16_f32 v67, v76, v77
	s_waitcnt vmcnt(8)
	v_cvt_pk_bf16_f32 v68, v78, v79
	v_cvt_pk_bf16_f32 v69, v80, v81
	ds_write2st64_b64 v117, v[66:67], v[68:69] offset0:40 offset1:44
	s_waitcnt vmcnt(7)
	v_cvt_pk_bf16_f32 v66, v82, v83
	v_cvt_pk_bf16_f32 v67, v84, v85
	s_waitcnt vmcnt(6)
	v_cvt_pk_bf16_f32 v68, v86, v87
	v_cvt_pk_bf16_f32 v69, v88, v89
	ds_write2st64_b64 v117, v[66:67], v[68:69] offset0:48 offset1:52
	s_waitcnt vmcnt(5)
	v_cvt_pk_bf16_f32 v66, v90, v91
	v_cvt_pk_bf16_f32 v67, v92, v93
	s_waitcnt vmcnt(4)
	v_cvt_pk_bf16_f32 v68, v94, v95
	v_cvt_pk_bf16_f32 v69, v96, v97
	ds_write2st64_b64 v117, v[66:67], v[68:69] offset0:56 offset1:60
	s_waitcnt vmcnt(3)
	ds_write_b128 v140, v[98:101] offset:51200
	s_waitcnt vmcnt(2)
	ds_write_b128 v140, v[102:105] offset:55808
	s_waitcnt vmcnt(1)
	ds_write_b128 v140, v[106:109] offset:60416
	s_waitcnt vmcnt(0)
	ds_write_b128 v140, v[110:113] offset:65024
	s_waitcnt lgkmcnt(0)
	s_barrier
	global_load_dwordx4 v[66:69], v[124:125], off
	global_load_dwordx4 v[70:73], v[126:127], off
	global_load_dwordx4 v[74:77], v[128:129], off
	global_load_dwordx4 v[78:81], v[130:131], off
	global_load_dwordx4 v[82:85], v[132:133], off
	global_load_dwordx4 v[86:89], v[134:135], off
	global_load_dwordx4 v[90:93], v[136:137], off
	global_load_dwordx4 v[94:97], v[138:139], off
	global_load_dwordx4 v[98:101], v[122:123], off
	global_load_dwordx4 v[102:105], v[154:155], off
	global_load_dwordx4 v[106:109], v[156:157], off
	global_load_dwordx4 v[110:113], v[158:159], off
	ds_read_b64_tr_b16 v[122:123], v121 offset:16384
	ds_read_b64_tr_b16 v[124:125], v121 offset:17408
	ds_read_b128 v[126:129], v0 offset:51200
	ds_read_b128 v[130:133], v0 offset:55808
	ds_read_b64_tr_b16 v[134:135], v119 offset:16384
	ds_read_b64_tr_b16 v[136:137], v119 offset:17408
	s_waitcnt lgkmcnt(2)
	v_mfma_f32_32x32x16_bf16 v[18:33], v[122:125], v[130:133], v[18:33]
	v_mfma_f32_32x32x16_bf16 v[50:65], v[122:125], v[126:129], v[50:65]
	s_waitcnt lgkmcnt(0)
	v_mfma_f32_32x32x16_bf16 v[34:49], v[134:137], v[126:129], v[34:49]
	ds_read_b64_tr_b16 v[122:123], v121 offset:20480
	ds_read_b64_tr_b16 v[124:125], v121 offset:21504
	ds_read_b128 v[126:129], v0 offset:51232
	v_mfma_f32_32x32x16_bf16 v[2:17], v[134:137], v[130:133], v[2:17]
	ds_read_b128 v[130:133], v0 offset:55840
	ds_read_b64_tr_b16 v[134:135], v119 offset:20480
	ds_read_b64_tr_b16 v[136:137], v119 offset:21504
	s_waitcnt lgkmcnt(3)
	v_mfma_f32_32x32x16_bf16 v[50:65], v[122:125], v[126:129], v[50:65]
	s_waitcnt lgkmcnt(2)
	v_mfma_f32_32x32x16_bf16 v[18:33], v[122:125], v[130:133], v[18:33]
	s_waitcnt lgkmcnt(0)
	v_mfma_f32_32x32x16_bf16 v[34:49], v[134:137], v[126:129], v[34:49]
	ds_read_b64_tr_b16 v[122:123], v121 offset:24576
	ds_read_b64_tr_b16 v[124:125], v121 offset:25600
	ds_read_b128 v[126:129], v0 offset:51264
	v_mfma_f32_32x32x16_bf16 v[2:17], v[134:137], v[130:133], v[2:17]
	ds_read_b128 v[130:133], v0 offset:55872
	ds_read_b64_tr_b16 v[134:135], v119 offset:24576
	ds_read_b64_tr_b16 v[136:137], v119 offset:25600
	s_waitcnt lgkmcnt(3)
	v_mfma_f32_32x32x16_bf16 v[50:65], v[122:125], v[126:129], v[50:65]
	s_waitcnt lgkmcnt(2)
	v_mfma_f32_32x32x16_bf16 v[18:33], v[122:125], v[130:133], v[18:33]
	s_waitcnt lgkmcnt(0)
	v_mfma_f32_32x32x16_bf16 v[34:49], v[134:137], v[126:129], v[34:49]
	ds_read_b64_tr_b16 v[122:123], v121 offset:28672
	ds_read_b64_tr_b16 v[124:125], v121 offset:29696
	ds_read_b128 v[126:129], v0 offset:51296
	v_mfma_f32_32x32x16_bf16 v[2:17], v[134:137], v[130:133], v[2:17]
	ds_read_b128 v[130:133], v0 offset:55904
	ds_read_b64_tr_b16 v[134:135], v119 offset:28672
	ds_read_b64_tr_b16 v[136:137], v119 offset:29696
	s_waitcnt lgkmcnt(3)
	v_mfma_f32_32x32x16_bf16 v[50:65], v[122:125], v[126:129], v[50:65]
	s_waitcnt lgkmcnt(2)
	v_mfma_f32_32x32x16_bf16 v[18:33], v[122:125], v[130:133], v[18:33]
	s_waitcnt lgkmcnt(0)
	v_mfma_f32_32x32x16_bf16 v[34:49], v[134:137], v[126:129], v[34:49]
	v_mfma_f32_32x32x16_bf16 v[2:17], v[134:137], v[130:133], v[2:17]
	s_lshl_b32 s0, s14, 1
	s_add_u32 s14, s22, s0
	s_addc_u32 s15, s23, 0
	s_ashr_i32 s0, s13, 1
	s_andn2_b32 s0, s0, 63
	s_waitcnt vmcnt(11)
	v_cvt_pk_bf16_f32 v66, v66, v67
	v_cvt_pk_bf16_f32 v67, v68, v69
	s_waitcnt vmcnt(10)
	v_cvt_pk_bf16_f32 v68, v70, v71
	v_cvt_pk_bf16_f32 v69, v72, v73
	s_ashr_i32 s1, s0, 31
	ds_write2st64_b64 v117, v[66:67], v[68:69] offset1:4
	s_waitcnt vmcnt(9)
	v_cvt_pk_bf16_f32 v66, v74, v75
	v_cvt_pk_bf16_f32 v67, v76, v77
	s_waitcnt vmcnt(8)
	v_cvt_pk_bf16_f32 v68, v78, v79
	v_cvt_pk_bf16_f32 v69, v80, v81
	s_lshl_b64 s[0:1], s[0:1], 1
	ds_write2st64_b64 v117, v[66:67], v[68:69] offset0:8 offset1:12
	s_waitcnt vmcnt(7)
	v_cvt_pk_bf16_f32 v66, v82, v83
	v_cvt_pk_bf16_f32 v67, v84, v85
	s_waitcnt vmcnt(6)
	v_cvt_pk_bf16_f32 v68, v86, v87
	v_cvt_pk_bf16_f32 v69, v88, v89
	s_add_u32 s0, s14, s0
	v_lshrrev_b32_e32 v0, 2, v115
	ds_write2st64_b64 v117, v[66:67], v[68:69] offset0:16 offset1:20
	s_waitcnt vmcnt(5)
	v_cvt_pk_bf16_f32 v66, v90, v91
	v_cvt_pk_bf16_f32 v67, v92, v93
	s_waitcnt vmcnt(4)
	v_cvt_pk_bf16_f32 v68, v94, v95
	v_cvt_pk_bf16_f32 v69, v96, v97
	s_addc_u32 s1, s15, s1
	v_and_b32_e32 v0, 8, v0
	ds_write2st64_b64 v117, v[66:67], v[68:69] offset0:24 offset1:28
	s_waitcnt vmcnt(3)
	ds_write_b128 v140, v[98:101] offset:32768
	s_waitcnt vmcnt(2)
	ds_write_b128 v140, v[102:105] offset:37376
	s_waitcnt vmcnt(1)
	ds_write_b128 v140, v[106:109] offset:41984
	s_waitcnt vmcnt(0)
	ds_write_b128 v140, v[110:113] offset:46592
	v_lshl_add_u64 v[66:67], s[0:1], 0, v[0:1]
	v_cmp_lt_i32_e32 vcc, -1, v120
	s_waitcnt lgkmcnt(0)
	s_barrier
	s_and_saveexec_b64 s[0:1], vcc
	s_cbranch_execz .LBB0_902
	v_mov_b32_e32 v121, v1
	v_lshlrev_b64 v[68:69], 11, v[120:121]
	v_pk_mul_f32 v[50:51], v[116:117], v[50:51] op_sel_hi:[0,1]
	v_pk_mul_f32 v[52:53], v[116:117], v[52:53] op_sel_hi:[0,1]
	v_pk_mul_f32 v[34:35], v[116:117], v[34:35] op_sel_hi:[0,1]
	v_pk_mul_f32 v[36:37], v[116:117], v[36:37] op_sel_hi:[0,1]
	v_lshl_add_u64 v[68:69], v[66:67], 0, v[68:69]
	v_cvt_pk_bf16_f32 v50, v50, v51
	v_cvt_pk_bf16_f32 v51, v52, v53
	v_cvt_pk_bf16_f32 v34, v34, v35
	v_cvt_pk_bf16_f32 v35, v36, v37
	global_store_dwordx2 v[68:69], v[50:51], off
	v_pk_mul_f32 v[50:51], v[116:117], v[54:55] op_sel_hi:[0,1]
	v_pk_mul_f32 v[52:53], v[116:117], v[56:57] op_sel_hi:[0,1]
	global_store_dwordx2 v[68:69], v[34:35], off offset:64
	v_pk_mul_f32 v[34:35], v[116:117], v[38:39] op_sel_hi:[0,1]
	v_pk_mul_f32 v[36:37], v[116:117], v[40:41] op_sel_hi:[0,1]
	v_cvt_pk_bf16_f32 v50, v50, v51
	v_cvt_pk_bf16_f32 v51, v52, v53
	v_cvt_pk_bf16_f32 v34, v34, v35
	v_cvt_pk_bf16_f32 v35, v36, v37
	global_store_dwordx2 v[68:69], v[50:51], off offset:16
	v_pk_mul_f32 v[50:51], v[116:117], v[58:59] op_sel_hi:[0,1]
	v_pk_mul_f32 v[52:53], v[116:117], v[60:61] op_sel_hi:[0,1]
	global_store_dwordx2 v[68:69], v[34:35], off offset:80
	v_pk_mul_f32 v[34:35], v[116:117], v[42:43] op_sel_hi:[0,1]
	v_pk_mul_f32 v[36:37], v[116:117], v[44:45] op_sel_hi:[0,1]
	v_cvt_pk_bf16_f32 v50, v50, v51
	v_cvt_pk_bf16_f32 v51, v52, v53
	v_cvt_pk_bf16_f32 v34, v34, v35
	v_cvt_pk_bf16_f32 v35, v36, v37
	global_store_dwordx2 v[68:69], v[50:51], off offset:32
	v_pk_mul_f32 v[50:51], v[116:117], v[62:63] op_sel_hi:[0,1]
	v_pk_mul_f32 v[52:53], v[116:117], v[64:65] op_sel_hi:[0,1]
	global_store_dwordx2 v[68:69], v[34:35], off offset:96
	v_pk_mul_f32 v[34:35], v[116:117], v[46:47] op_sel_hi:[0,1]
	v_pk_mul_f32 v[36:37], v[116:117], v[48:49] op_sel_hi:[0,1]
	v_cvt_pk_bf16_f32 v50, v50, v51
	v_cvt_pk_bf16_f32 v51, v52, v53
	v_cvt_pk_bf16_f32 v34, v34, v35
	v_cvt_pk_bf16_f32 v35, v36, v37
	global_store_dwordx2 v[68:69], v[50:51], off offset:48
	global_store_dwordx2 v[68:69], v[34:35], off offset:112

	.amdhsa_kernel _Z14fwd_megakernel6Params
		.amdhsa_group_segment_fixed_size 78368
		.amdhsa_private_segment_fixed_size 0
		.amdhsa_kernarg_size 440
		.amdhsa_user_sgpr_count 2
		.amdhsa_user_sgpr_dispatch_ptr 0
		.amdhsa_user_sgpr_queue_ptr 0
		.amdhsa_user_sgpr_kernarg_segment_ptr 1
		.amdhsa_user_sgpr_dispatch_id 0
		.amdhsa_user_sgpr_kernarg_preload_length 0
		.amdhsa_user_sgpr_kernarg_preload_offset 0
		.amdhsa_user_sgpr_private_segment_size 0
		.amdhsa_uses_dynamic_stack 0
		.amdhsa_enable_private_segment 0
		.amdhsa_system_sgpr_workgroup_id_x 1
		.amdhsa_system_sgpr_workgroup_id_y 0
		.amdhsa_system_sgpr_workgroup_id_z 0
		.amdhsa_system_sgpr_workgroup_info 0
		.amdhsa_system_vgpr_workitem_id 2
		.amdhsa_next_free_vgpr 254
		.amdhsa_next_free_sgpr 102
		.amdhsa_accum_offset 256
		.amdhsa_reserve_vcc 1
		.amdhsa_float_round_mode_32 0
		.amdhsa_float_round_mode_16_64 0
		.amdhsa_float_denorm_mode_32 3
		.amdhsa_float_denorm_mode_16_64 3
		.amdhsa_dx10_clamp 1
		.amdhsa_ieee_mode 1
		.amdhsa_fp16_overflow 0
		.amdhsa_tg_split 0
		.amdhsa_exception_fp_ieee_invalid_op 0
		.amdhsa_exception_fp_denorm_src 0
		.amdhsa_exception_fp_ieee_div_zero 0
		.amdhsa_exception_fp_ieee_overflow 0
		.amdhsa_exception_fp_ieee_underflow 0
		.amdhsa_exception_fp_ieee_inexact 0
		.amdhsa_exception_int_div_zero 0
	.end_amdhsa_kernel

amdhsa.kernels:
  - .agpr_count:     0
    .args:
      - .offset:         0
        .size:           184
        .value_kind:     by_value
      - .offset:         184
        .size:           4
        .value_kind:     hidden_block_count_x
      - .offset:         188
        .size:           4
        .value_kind:     hidden_block_count_y
      - .offset:         192
        .size:           4
        .value_kind:     hidden_block_count_z
      - .offset:         196
        .size:           2
        .value_kind:     hidden_group_size_x
      - .offset:         198
        .size:           2
        .value_kind:     hidden_group_size_y
      - .offset:         200
        .size:           2
        .value_kind:     hidden_group_size_z
      - .offset:         202
        .size:           2
        .value_kind:     hidden_remainder_x
      - .offset:         204
        .size:           2
        .value_kind:     hidden_remainder_y
      - .offset:         206
        .size:           2
        .value_kind:     hidden_remainder_z
      - .offset:         224
        .size:           8
        .value_kind:     hidden_global_offset_x
      - .offset:         232
        .size:           8
        .value_kind:     hidden_global_offset_y
      - .offset:         240
        .size:           8
        .value_kind:     hidden_global_offset_z
      - .offset:         248
        .size:           2
        .value_kind:     hidden_grid_dims
      - .offset:         272
        .size:           8
        .value_kind:     hidden_multigrid_sync_arg
    .group_segment_fixed_size: 78368
    .kernarg_segment_align: 8
    .kernarg_segment_size: 440
    .language:       OpenCL C
    .language_version:
      - 2
      - 0
    .max_flat_workgroup_size: 256
    .name:           _Z14fwd_megakernel6Params
    .private_segment_fixed_size: 0
    .sgpr_count:     108
    .sgpr_spill_count: 165
    .symbol:         _Z14fwd_megakernel6Params.kd
    .uniform_work_group_size: 1
    .uses_dynamic_stack: false
    .vgpr_count:     254
    .vgpr_spill_count: 0
    .wavefront_size: 64
